# up-GEMM GLU epilogue: conv weights staged to LDS by LDS-DMA per unit, ds_read instead of global loads, global stores, no vmcnt(0) waits
# speedup vs baseline: 1.0136x; 1.0136x over previous
; #define PG8_STAGE(bufoff, gbase, voff) do { _Pragma("unroll") for (int _i = 0; _i < 2; ++_i) \
;         __builtin_amdgcn_global_load_lds((const unsigned*)((const char*)(gbase) + (voff)[_i]), (PG8_LAS unsigned*)(lds + (bufoff) + ldsw + _i * 8192), 16, 0, 0); } while (0)
; #define PG8_WAIT_V(n) asm volatile("s_waitcnt vmcnt(" #n ")" ::: "memory")
; #define PG8_BAR __builtin_amdgcn_s_barrier()
;     __device__ __forceinline__ void operator()(const f32x4 (&acc)[2][2][4][2], const Unit& u, int wr, int wc, int fr_, int fq_) const {
;     ...
;                 const f32x4 wg0 = *(const f32x4*)(cw + j), wg1 = *(const f32x4*)(cw + 5632 + j), wg2 = *(const f32x4*)(cw + 2 * 5632 + j), bg = *(const f32x4*)(cb + j);
;                 const f32x4 wv0 = *(const f32x4*)(cw + 2816 + j), wv1 = *(const f32x4*)(cw + 5632 + 2816 + j), wv2 = *(const f32x4*)(cw + 2 * 5632 + 2816 + j), bv = *(const f32x4*)(cb + 2816 + j);
; template <class Epi, class Sched, bool ALIGN_EPI = false, bool SP2 = false, bool MID = false>
; __device__ __forceinline__ void gemm_phase(PG8_LAS unsigned char* lds, const Gemm g, const Sched& S, const Epi& E, const PG8_LAS float* mid = nullptr) {
;     ...
;     const char* cA = (const char*)g.A + (size_t)cur.pm * tstepA; const char* cB = (const char*)g.Bt + (size_t)cur.pn * tstepB;
;     S.a_ready(cur);
;     if constexpr (SP2) {
;         PG8_STAGE(PG8_SB(0, 0), cB, voffB); PG8_STAGE(PG8_SB(0, 1), cB + hstepB, voffB); PG8_STAGE(PG8_SA(0, 0), cA, voffA); PG8_STAGE(PG8_SA(0, 1), cA + hstepA, voffA);
;         if (wr == 1) PG8_BAR;
;         PG8_WAIT_V(2); PG8_BAR;
;         PG8_STAGE(PG8_SB(1, 0), cB + kstep, voffB); PG8_STAGE(PG8_SA(1, 0), cA + kstep, voffA); PG8_STAGE(PG8_SB(1, 1), cB + hstepB + kstep, voffB);
;         PG8_WAIT_V(6); PG8_BAR;
;     } else {
;         PG8_STAGE(PG8_SB(0, 0), cB, voffB); PG8_STAGE(PG8_SA(0, 0), cA, voffA); PG8_STAGE(PG8_SB(0, 1), cB + hstepB, voffB); PG8_STAGE(PG8_SA(0, 1), cA + hstepA, voffA);
;         if (wr == 1) PG8_BAR;
;         PG8_WAIT_V(4); PG8_BAR;
;         PG8_STAGE(PG8_SB(1, 0), cB + kstep, voffB); PG8_STAGE(PG8_SA(1, 0), cA + kstep, voffA); PG8_STAGE(PG8_SB(1, 1), cB + hstepB + kstep, voffB);
;         PG8_WAIT_V(6); PG8_BAR;
;     }
.LBB0_553:
	s_add_u32 s79, s36, 0x7400000
	s_addc_u32 s84, s37, 0
	s_add_u32 s94, s36, 0x17400000
	s_addc_u32 s5, s37, 0
	v_bfe_u32 v219, v12, 4, 2
	v_writelane_b32 v255, s5, 43
	v_and_b32_e32 v187, 15, v12
	s_lshl_b32 s5, s40, 6
	v_lshlrev_b32_e32 v15, 4, v219
	v_lshlrev_b32_e32 v12, 2, v12
	v_writelane_b32 v255, s5, 44
	v_lshl_or_b32 v15, v187, 6, v15
	s_lshl_b32 s5, s40, 13
	v_and_b32_e32 v12, 32, v12
	v_bitop3_b32 v16, v15, s5, v12 bitop3:0xde
	s_lshl_b32 s5, s41, 5
	s_and_b32 s5, s5, 0x60
	s_add_i32 m0, s19, 0x18000
	v_lshl_add_u64 v[4:5], v[4:5], 0, s[16:17]
	s_mov_b32 s92, s5
	s_lshl_b32 s5, s5, 7
	s_waitcnt vmcnt(2)
	s_barrier
	global_load_lds_dwordx4 v[4:5], off
	v_lshl_add_u64 v[2:3], v[2:3], 0, s[16:17]
	s_add_i32 m0, s19, 0x1a000
	s_add_i32 s48, s19, 0x8000
	s_add_i32 s49, s19, 0xa000
	global_load_lds_dwordx4 v[2:3], off
	v_lshl_add_u64 v[0:1], v[0:1], 0, s[16:17]
	s_mov_b32 m0, s48
	s_add_u32 s36, s38, 0x40080
	global_load_lds_dwordx4 v[0:1], off
	v_lshl_add_u64 v[0:1], v[6:7], 0, s[16:17]
	s_mov_b32 m0, s49
	s_addc_u32 s37, s39, 0
	global_load_lds_dwordx4 v[0:1], off
	s_add_i32 m0, s19, 0x1c000
	v_lshl_add_u64 v[0:1], s[36:37], 0, v[176:177]
	global_load_lds_dwordx4 v[0:1], off
	v_lshl_add_u64 v[0:1], s[36:37], 0, v[180:181]
	s_add_i32 m0, s19, 0x1e000
	s_cmpk_lt_u32 s3, 0x100
	global_load_lds_dwordx4 v[0:1], off
	s_cselect_b64 s[36:37], -1, 0
	s_ashr_i32 s89, s10, 31
	s_ashr_i32 s3, s82, 31
	s_add_u32 s50, s44, 0x5800
	s_addc_u32 s51, s45, 0
	s_add_u32 s52, s44, 0xb000
	s_addc_u32 s53, s45, 0
	v_lshlrev_b32_e32 v0, 14, v8
	s_add_u32 s54, s44, 0x2c00
	v_and_b32_e32 v0, 0xffff8000, v0
	s_addc_u32 s55, s45, 0
	v_lshl_add_u32 v0, v9, 11, v0
	v_and_b32_e32 v1, 1, v8
	s_add_u32 s56, s44, 0x8400
	v_lshl_or_b32 v0, v1, 6, v0
	s_addc_u32 s57, s45, 0
	v_lshl_add_u32 v182, v10, 1, v0
	v_lshlrev_b32_e32 v0, 14, v11
	s_add_u32 s58, s44, 0xdc00
	v_and_b32_e32 v0, 0xffff8000, v0
	s_waitcnt vmcnt(6)
	v_writelane_b32 v255, s36, 47
	s_addc_u32 s59, s45, 0
	v_lshl_add_u32 v0, v13, 11, v0
	v_and_b32_e32 v1, 1, v11
	v_writelane_b32 v255, s37, 48
	s_add_u32 s60, s14, 0x2c00
	v_lshl_or_b32 v0, v1, 6, v0
	v_bitop3_b32 v220, v15, s5, v12 bitop3:0xde
	v_writelane_b32 v255, s3, 45
	s_addc_u32 s61, s15, 0
	s_lshr_b32 s100, s85, 1
	s_mov_b64 s[98:99], s[44:45]
	s_cmp_eq_u32 s100, 512
	s_cselect_b32 s98, s50, s98
	s_cselect_b32 s99, s51, s99
	s_cmp_eq_u32 s100, 1024
	s_cselect_b32 s98, s52, s98
	s_cselect_b32 s99, s53, s99
	s_cmp_eq_u32 s100, 1536
	s_cselect_b32 s98, s14, s98
	s_cselect_b32 s99, s15, s99
	s_cmp_eq_u32 s100, 2048
	s_cselect_b32 s98, s54, s98
	s_cselect_b32 s99, s55, s99
	s_cmp_eq_u32 s100, 2560
	s_cselect_b32 s98, s56, s98
	s_cselect_b32 s99, s57, s99
	s_cmp_eq_u32 s100, 3072
	s_cselect_b32 s98, s58, s98
	s_cselect_b32 s99, s59, s99
	s_cmp_eq_u32 s100, 3584
	s_cselect_b32 s98, s60, s98
	s_cselect_b32 s99, s61, s99
	s_add_i32 s100, s100, 0x22000
	v_mov_b32_e32 v183, v81
	v_lshl_add_u32 v184, v14, 1, v0
	v_mov_b32_e32 v185, v81
	s_mov_b32 s78, 0
	v_add_u32_e32 v221, 0, v16
	s_barrier
	s_branch .LBB0_556

; template <class Epi, class Sched, bool ALIGN_EPI = false, bool SP2 = false, bool MID = false>
; __device__ __forceinline__ void gemm_phase(PG8_LAS unsigned char* lds, const Gemm g, const Sched& S, const Epi& E, const PG8_LAS float* mid = nullptr) {
;     ...
;         const bool has_next = S.next(ui + 1, nxt);
;         const char* nA = has_next ? (const char*)g.A + (size_t)nxt.pm * tstepA : cA; const char* nB = has_next ? (const char*)g.Bt + (size_t)nxt.pn * tstepB : cB;
;     ...
; #pragma unroll
;         for (int a = 0; a < 2; ++a)
; #pragma unroll
;             for (int b = 0; b < 2; ++b)
; #pragma unroll
;                 for (int m = 0; m < 4; ++m)
; #pragma unroll
;                     for (int n = 0; n < 2; ++n) acc[a][b][m][n] = (f32x4){0.f, 0.f, 0.f, 0.f};
;         cur = nxt; cA = nA; cB = nB; ++ui;
.LBB0_558:
	s_lshl_b32 s101, s4, 9
	v_lshlrev_b32_e32 v130, 2, v162
	v_add_u32_e32 v130, s101, v130
	s_xor_b32 s100, s100, 0x1000
	s_and_b32 s101, s100, 0xfffff1ff
	s_mov_b32 m0, s100
	s_nop 0
	global_load_lds_dword v130, s[98:99]
	global_load_lds_dword v130, s[98:99] offset:256
	s_ashr_i32 s65, s64, 31
	s_lshl_b64 s[40:41], s[64:65], 19
	s_add_u32 s66, s88, s40
	s_addc_u32 s67, s93, s41
	s_and_b64 s[40:41], s[36:37], exec
	s_cselect_b32 s5, s67, s13
	s_cselect_b32 s21, s66, s12
	s_ashr_i32 s63, s62, 31
	s_lshl_b64 s[40:41], s[62:63], 19
	s_add_u32 s68, s83, s40
	s_addc_u32 s69, s87, s41
	s_and_b64 s[40:41], s[36:37], exec
	s_cselect_b32 s42, s69, s39
	s_cselect_b32 s43, s68, s38
	s_add_u32 s12, s12, 0x40080
	s_addc_u32 s13, s13, 0
	s_add_u32 s63, s38, 0x100
	v_mov_b32_e32 v0, 0
	s_addc_u32 s65, s39, 0
	s_mov_b32 s70, -2
	v_mov_b32_e32 v1, v0
	v_mov_b32_e32 v2, v0
	v_mov_b32_e32 v3, v0
	v_mov_b32_e32 v32, v0
	v_mov_b32_e32 v33, v0
	v_mov_b32_e32 v34, v0
	v_mov_b32_e32 v35, v0
	v_mov_b32_e32 v8, v0
	v_mov_b32_e32 v9, v0
	v_mov_b32_e32 v10, v0
	v_mov_b32_e32 v11, v0
	v_mov_b32_e32 v40, v0
	v_mov_b32_e32 v41, v0
	v_mov_b32_e32 v42, v0
	v_mov_b32_e32 v43, v0
	v_mov_b32_e32 v16, v0
	v_mov_b32_e32 v17, v0
	v_mov_b32_e32 v18, v0
	v_mov_b32_e32 v19, v0
	v_mov_b32_e32 v48, v0
	v_mov_b32_e32 v49, v0
	v_mov_b32_e32 v50, v0
	v_mov_b32_e32 v51, v0
	v_mov_b32_e32 v24, v0
	v_mov_b32_e32 v25, v0
	v_mov_b32_e32 v26, v0
	v_mov_b32_e32 v27, v0
	v_mov_b32_e32 v56, v0
	v_mov_b32_e32 v57, v0
	v_mov_b32_e32 v58, v0
	v_mov_b32_e32 v59, v0
	v_mov_b32_e32 v4, v0
	v_mov_b32_e32 v5, v0
	v_mov_b32_e32 v6, v0
	v_mov_b32_e32 v7, v0
	v_mov_b32_e32 v36, v0
	v_mov_b32_e32 v37, v0
	v_mov_b32_e32 v38, v0
	v_mov_b32_e32 v39, v0
	v_mov_b32_e32 v12, v0
	v_mov_b32_e32 v13, v0
	v_mov_b32_e32 v14, v0
	v_mov_b32_e32 v15, v0
	v_mov_b32_e32 v44, v0
	v_mov_b32_e32 v45, v0
	v_mov_b32_e32 v46, v0
	v_mov_b32_e32 v47, v0
	v_mov_b32_e32 v20, v0
	v_mov_b32_e32 v21, v0
	v_mov_b32_e32 v22, v0
	v_mov_b32_e32 v23, v0
	v_mov_b32_e32 v52, v0
	v_mov_b32_e32 v53, v0
	v_mov_b32_e32 v54, v0
	v_mov_b32_e32 v55, v0
	v_mov_b32_e32 v28, v0
	v_mov_b32_e32 v29, v0
	v_mov_b32_e32 v30, v0
	v_mov_b32_e32 v31, v0
	v_mov_b32_e32 v60, v0
	v_mov_b32_e32 v61, v0
	v_mov_b32_e32 v62, v0
	v_mov_b32_e32 v63, v0
	v_mov_b32_e32 v64, v0
	v_mov_b32_e32 v65, v0
	v_mov_b32_e32 v66, v0
	v_mov_b32_e32 v67, v0
	v_mov_b32_e32 v98, v0
	v_mov_b32_e32 v99, v0
	v_mov_b32_e32 v100, v0
	v_mov_b32_e32 v101, v0
	v_mov_b32_e32 v72, v0
	v_mov_b32_e32 v73, v0
	v_mov_b32_e32 v74, v0
	v_mov_b32_e32 v75, v0
	v_mov_b32_e32 v106, v0
	v_mov_b32_e32 v107, v0
	v_mov_b32_e32 v108, v0
	v_mov_b32_e32 v109, v0
	v_mov_b32_e32 v82, v0
	v_mov_b32_e32 v83, v0
	v_mov_b32_e32 v84, v0
	v_mov_b32_e32 v85, v0
	v_mov_b32_e32 v114, v0
	v_mov_b32_e32 v115, v0
	v_mov_b32_e32 v116, v0
	v_mov_b32_e32 v117, v0
	v_mov_b32_e32 v90, v0
	v_mov_b32_e32 v91, v0
	v_mov_b32_e32 v92, v0
	v_mov_b32_e32 v93, v0
	v_mov_b32_e32 v122, v0
	v_mov_b32_e32 v123, v0
	v_mov_b32_e32 v124, v0
	v_mov_b32_e32 v125, v0
	v_mov_b32_e32 v68, v0
	v_mov_b32_e32 v69, v0
	v_mov_b32_e32 v70, v0
	v_mov_b32_e32 v71, v0
	v_mov_b32_e32 v102, v0
	v_mov_b32_e32 v103, v0
	v_mov_b32_e32 v104, v0
	v_mov_b32_e32 v105, v0
	v_mov_b32_e32 v76, v0
	v_mov_b32_e32 v77, v0
	v_mov_b32_e32 v78, v0
	v_mov_b32_e32 v79, v0
	v_mov_b32_e32 v110, v0
	v_mov_b32_e32 v111, v0
	v_mov_b32_e32 v112, v0
	v_mov_b32_e32 v113, v0
	v_mov_b32_e32 v86, v0
	v_mov_b32_e32 v87, v0
	v_mov_b32_e32 v88, v0
	v_mov_b32_e32 v89, v0
	v_mov_b32_e32 v118, v0
	v_mov_b32_e32 v119, v0
	v_mov_b32_e32 v120, v0
	v_mov_b32_e32 v121, v0
	v_mov_b32_e32 v94, v0
	v_mov_b32_e32 v95, v0
	v_mov_b32_e32 v96, v0
	v_mov_b32_e32 v97, v0
	v_mov_b32_e32 v126, v0
	v_mov_b32_e32 v127, v0
	v_mov_b32_e32 v128, v0
	v_mov_b32_e32 v129, v0

;     __device__ __forceinline__ void operator()(const f32x4 (&acc)[2][2][4][2], const Unit& u, int wr, int wc, int fr_, int fq_) const {
;     ...
;         const int rowu = u.pm * BM + wr * 64;
;         const int jbase = u.pn * 128 + wc * 32 + 8 * fq;
;         const unsigned ecol = (unsigned)(u.pn * BM + wc * 32 + 8 * fq);
; #pragma unroll
;         for (int ai = 0; ai < 2; ++ai) {
;             const int grp = (rowu + ai * HALF) >> 6;
; #pragma unroll
;             for (int mm = 0; mm < 2; ++mm) { const int m = mm * 3;
;                 const bool is_edge = mm == 0 ? (fr < 2) : (fr >= 14);
;                 if (is_edge) { const unsigned e = (unsigned)(mm == 0 ? fr : fr - 12);
;                     bf16_t* eb = edge + (size_t)grp * 4 * 5632;
; #pragma unroll
;                     for (int bj = 0; bj < 2; ++bj) { const f32x4 v0 = acc[ai][bj][m][0], v1 = acc[ai][bj][m][1];
;                         u32x4 w; w.x = cvt_pk_bf16(v0[0], v0[1]); w.y = cvt_pk_bf16(v0[2], v0[3]); w.z = cvt_pk_bf16(v1[0], v1[1]); w.w = cvt_pk_bf16(v1[2], v1[3]);
;                         *(u32x4*)(eb + (e * 5632u + ecol + (unsigned)(bj * HALF))) = w; } } }
; #pragma unroll
;             for (int n = 0; n < 2; ++n) {
;                 int jl = jbase + 4 * n; asm volatile("" : "+v"(jl) :: "memory");
;                 const unsigned j = (unsigned)jl;
;                 const f32x4 wg0 = *(const f32x4*)(cw + j), wg1 = *(const f32x4*)(cw + 5632 + j), wg2 = *(const f32x4*)(cw + 2 * 5632 + j), bg = *(const f32x4*)(cb + j);
;                 const f32x4 wv0 = *(const f32x4*)(cw + 2816 + j), wv1 = *(const f32x4*)(cw + 5632 + 2816 + j), wv2 = *(const f32x4*)(cw + 2 * 5632 + 2816 + j), bv = *(const f32x4*)(cb + 2816 + j);
;                 const unsigned loff = (unsigned)fr * 2816u + j;
;                 const bool c1 = fr == 0, c2 = fr < 2;
;                 f32x4 g1p = (f32x4){0.f, 0.f, 0.f, 0.f}, g2p = g1p, v1p = g1p, v2p = g1p;
; #pragma unroll
;                 for (int m = 0; m < 4; ++m) {
;                     const f32x4 xg = acc[ai][0][m][n], xv = acc[ai][1][m][n];
;                     f32x4 g1, g2, v1, v2;
; #pragma unroll
;                     for (int i = 0; i < 4; ++i) { g1[i] = dpp_ror1(xg[i]); g2[i] = dpp_ror2(xg[i]); v1[i] = dpp_ror1(xv[i]); v2[i] = dpp_ror2(xv[i]); }
;                     f32x4 pg1, pg2, pv1, pv2;
; #pragma unroll
.LBB0_562:
	s_lshl_b32 s63, s20, 8
	v_readlane_b32 s3, v255, 44
	v_mov_b32_e32 v189, v187
	v_mov_b32_e32 v80, v219
	s_add_i32 s63, s63, s3
	s_lshl_b32 s3, s4, 8
	s_or_b32 s3, s3, s92
	v_lshlrev_b32_e32 v130, 3, v80
	s_ashr_i32 s5, s63, 6
	v_add_u32_e32 v186, s3, v130
	v_cmp_lt_i32_e64 s[40:41], 1, v189
	v_cmp_gt_i32_e32 vcc, 2, v189
	s_mul_hi_i32 s3, s5, 0xb000
	s_mul_i32 s5, s5, 0xb000
	s_and_saveexec_b64 s[12:13], vcc
	s_cbranch_execz .LBB0_564
	s_movk_i32 s38, 0x1600
	s_add_u32 s20, s94, s5
	v_readlane_b32 s21, v255, 43
	v_mad_u64_u32 v[136:137], s[38:39], v189, s38, v[186:187]
	s_addc_u32 s21, s21, s3
	v_mov_b32_e32 v137, v81
	v_cvt_pk_bf16_f32 v132, v126, v127
	v_cvt_pk_bf16_f32 v133, v128, v129
	v_cvt_pk_bf16_f32 v134, v94, v95
	v_cvt_pk_bf16_f32 v135, v96, v97
	v_lshl_add_u64 v[138:139], v[136:137], 1, s[20:21]
	v_add_u32_e32 v80, 0x80, v136
	global_store_dwordx4 v[138:139], v[132:135], off
	v_lshl_add_u64 v[136:137], v[80:81], 1, s[20:21]
	s_nop 0
	v_cvt_pk_bf16_f32 v132, v122, v123
	v_cvt_pk_bf16_f32 v133, v124, v125
	v_cvt_pk_bf16_f32 v134, v90, v91
	v_cvt_pk_bf16_f32 v135, v92, v93
	global_store_dwordx4 v[136:137], v[132:135], off
.LBB0_564:
	s_or_b64 exec, exec, s[12:13]
	v_cmp_lt_i32_e64 s[42:43], 13, v189
	v_add_u32_e32 v223, -12, v189
	s_and_saveexec_b64 s[12:13], s[42:43]
	s_cbranch_execz .LBB0_566
	s_add_u32 s20, s94, s5
	v_readlane_b32 s5, v255, 43
	s_addc_u32 s21, s5, s3
	s_movk_i32 s3, 0x1600
	v_mad_u64_u32 v[136:137], s[38:39], v223, s3, v[186:187]
	v_mov_b32_e32 v137, v81
	v_cvt_pk_bf16_f32 v132, v102, v103
	v_cvt_pk_bf16_f32 v133, v104, v105
	v_cvt_pk_bf16_f32 v134, v68, v69
	v_cvt_pk_bf16_f32 v135, v70, v71
	v_lshl_add_u64 v[138:139], v[136:137], 1, s[20:21]
	v_add_u32_e32 v80, 0x80, v136
	global_store_dwordx4 v[138:139], v[132:135], off
	v_lshl_add_u64 v[136:137], v[80:81], 1, s[20:21]
	s_nop 0
	v_cvt_pk_bf16_f32 v132, v98, v99
	v_cvt_pk_bf16_f32 v133, v100, v101
	v_cvt_pk_bf16_f32 v134, v64, v65
	v_cvt_pk_bf16_f32 v135, v66, v67
	global_store_dwordx4 v[136:137], v[132:135], off
.LBB0_566:
	s_or_b64 exec, exec, s[12:13]
	s_lshl_b32 s3, s4, 7
	s_or_b32 s3, s3, s92
	v_add_u32_e32 v188, s3, v130
	v_mov_b32_e32 v80, v188
	s_movk_i32 s3, 0xb00
	v_lshlrev_b32_e32 v138, 2, v80
	v_and_b32_e32 v138, 0x1ff, v138
	v_add_u32_e32 v138, s101, v138
	ds_read_b128 v[158:161], v138 offset:0
	ds_read_b128 v[150:153], v138 offset:512
	ds_read_b128 v[146:149], v138 offset:1024
	ds_read_b128 v[154:157], v138 offset:1536
	ds_read_b128 v[142:145], v138 offset:2048
	s_nop 0
	ds_read_b128 v[130:133], v138 offset:2560
	v_mul_lo_u32 v222, v189, s3
	ds_read_b128 v[134:137], v138 offset:3072
	v_add_u32_e32 v80, v80, v222
	ds_read_b128 v[138:141], v138 offset:3584
	v_mov_b32_dpp v202, v126 row_ror:1 row_mask:0xf bank_mask:0xf
	v_mov_b32_dpp v204, v126 row_ror:2 row_mask:0xf bank_mask:0xf
	v_mov_b32_dpp v196, v122 row_ror:1 row_mask:0xf bank_mask:0xf
	v_mov_b32_dpp v200, v122 row_ror:2 row_mask:0xf bank_mask:0xf
	v_mov_b32_dpp v203, v127 row_ror:1 row_mask:0xf bank_mask:0xf
	v_mov_b32_dpp v205, v127 row_ror:2 row_mask:0xf bank_mask:0xf
	v_mov_b32_dpp v197, v123 row_ror:1 row_mask:0xf bank_mask:0xf
	v_mov_b32_dpp v201, v123 row_ror:2 row_mask:0xf bank_mask:0xf
	v_mov_b32_dpp v194, v128 row_ror:1 row_mask:0xf bank_mask:0xf
	v_mov_b32_dpp v198, v128 row_ror:2 row_mask:0xf bank_mask:0xf
	v_mov_b32_dpp v190, v124 row_ror:1 row_mask:0xf bank_mask:0xf
	v_mov_b32_dpp v192, v124 row_ror:2 row_mask:0xf bank_mask:0xf
	v_mov_b32_dpp v195, v129 row_ror:1 row_mask:0xf bank_mask:0xf
	v_mov_b32_dpp v199, v129 row_ror:2 row_mask:0xf bank_mask:0xf
	v_mov_b32_dpp v191, v125 row_ror:1 row_mask:0xf bank_mask:0xf
	v_mov_b32_dpp v193, v125 row_ror:2 row_mask:0xf bank_mask:0xf
	s_mul_i32 s65, s63, 0x1600
	s_and_saveexec_b64 s[4:5], s[40:41]
	s_xor_b64 s[4:5], exec, s[4:5]
	s_cbranch_execz .LBB0_568
	s_waitcnt lgkmcnt(0)
	v_pk_mul_f32 v[210:211], v[158:159], v[204:205]
	v_pk_mul_f32 v[212:213], v[142:143], v[200:201]
	v_pk_fma_f32 v[210:211], v[150:151], v[202:203], v[210:211]
	v_pk_fma_f32 v[212:213], v[130:131], v[196:197], v[212:213]
	v_pk_fma_f32 v[126:127], v[126:127], v[146:147], v[210:211]
	v_pk_fma_f32 v[122:123], v[122:123], v[134:135], v[212:213]
	v_pk_add_f32 v[126:127], v[154:155], v[126:127]
	v_pk_add_f32 v[122:123], v[138:139], v[122:123]
	v_mul_f32_e32 v210, 0xbfb8aa3b, v126
	v_mul_f32_e32 v211, 0xbfb8aa3b, v127
	v_exp_f32_e32 v210, v210
	v_exp_f32_e32 v211, v211
	s_mul_hi_i32 s3, s63, 0x1600
	s_add_u32 s12, s79, s65
	v_add_f32_e32 v210, 1.0, v210
	v_add_f32_e32 v211, 1.0, v211
	v_rcp_f32_e32 v210, v210
	v_rcp_f32_e32 v211, v211
	s_addc_u32 s13, s84, s3
	v_pk_mul_f32 v[126:127], v[126:127], v[210:211]
	s_nop 0
	v_pk_mul_f32 v[122:123], v[122:123], v[126:127]
	v_pk_mul_f32 v[126:127], v[160:161], v[198:199]
	v_pk_mul_f32 v[210:211], v[144:145], v[192:193]
	v_pk_fma_f32 v[126:127], v[152:153], v[194:195], v[126:127]
	v_pk_fma_f32 v[210:211], v[132:133], v[190:191], v[210:211]
	v_pk_fma_f32 v[126:127], v[128:129], v[148:149], v[126:127]
	v_pk_fma_f32 v[124:125], v[124:125], v[136:137], v[210:211]
	v_pk_add_f32 v[126:127], v[156:157], v[126:127]
	v_pk_add_f32 v[124:125], v[140:141], v[124:125]
	v_mul_f32_e32 v128, 0xbfb8aa3b, v126
	v_mul_f32_e32 v129, 0xbfb8aa3b, v127
	v_exp_f32_e32 v128, v128
	v_exp_f32_e32 v129, v129
	v_add_f32_e32 v128, 1.0, v128
	v_add_f32_e32 v129, 1.0, v129
	v_rcp_f32_e32 v128, v128
	v_rcp_f32_e32 v129, v129
	s_nop 0
	v_pk_mul_f32 v[126:127], v[126:127], v[128:129]
	s_nop 0
	v_pk_mul_f32 v[124:125], v[124:125], v[126:127]
	s_nop 0
	v_cvt_pk_bf16_f32 v125, v124, v125
	v_cvt_pk_bf16_f32 v124, v122, v123
	v_lshl_add_u64 v[122:123], v[80:81], 1, s[12:13]
	global_store_dwordx2 v[122:123], v[124:125], off
; __device__ __forceinline__ unsigned cvt_pk_bf16(float lo, float hi) { f32x2_cv v = {lo, hi}; bf16x2_cv b = __builtin_convertvector(v, bf16x2_cv); return __builtin_bit_cast(unsigned, b); }
; __device__ __forceinline__ float dpp_ror1(float v) { return __builtin_bit_cast(float, __builtin_amdgcn_mov_dpp(__builtin_bit_cast(int, v), 0x121, 0xf, 0xf, false)); }
; __device__ __forceinline__ float dpp_ror2(float v) { return __builtin_bit_cast(float, __builtin_amdgcn_mov_dpp(__builtin_bit_cast(int, v), 0x122, 0xf, 0xf, false)); }
;     __device__ __forceinline__ void operator()(const f32x4 (&acc)[2][2][4][2], const Unit& u, int wr, int wc, int fr_, int fq_) const {
;     ...
;                 for (int m = 0; m < 4; ++m) {
;                     const f32x4 xg = acc[ai][0][m][n], xv = acc[ai][1][m][n];
;                     f32x4 g1, g2, v1, v2;
; #pragma unroll
;                     for (int i = 0; i < 4; ++i) { g1[i] = dpp_ror1(xg[i]); g2[i] = dpp_ror2(xg[i]); v1[i] = dpp_ror1(xv[i]); v2[i] = dpp_ror2(xv[i]); }
;                     f32x4 pg1, pg2, pv1, pv2;
; #pragma unroll
;                     for (int i = 0; i < 4; ++i) { pg1[i] = c1 ? g1p[i] : g1[i]; pg2[i] = c2 ? g2p[i] : g2[i]; pv1[i] = c1 ? v1p[i] : v1[i]; pv2[i] = c2 ? v2p[i] : v2[i]; }
;                     const f32x4 G = wg0 * pg2 + wg1 * pg1 + wg2 * xg + bg;
;                     const f32x4 V = wv0 * pv2 + wv1 * pv1 + wv2 * xv + bv;
;                     f32x4 r;
; #pragma unroll
;                     for (int i = 0; i < 4; ++i) r[i] = G[i] * __builtin_amdgcn_rcpf(1.0f + __builtin_amdgcn_exp2f(-1.4426950408889634f * G[i])) * V[i];
;                     u32x2 w; w.x = cvt_pk_bf16(r[0], r[1]); w.y = cvt_pk_bf16(r[2], r[3]);
;                     if (m > 0 || !c2) *(u32x2*)(ACT + (size_t)(rowu + ai * HALF + m * 16) * 2816 + loff) = w;
;                     g1p = g1; g2p = g2; v1p = v1; v2p = v2;
.LBB0_568:
	s_andn2_saveexec_b64 s[4:5], s[4:5]
	s_or_b64 exec, exec, s[4:5]
	v_cmp_eq_u32_e64 s[38:39], 0, v189
	v_mov_b32_dpp v129, v118 row_ror:2 row_mask:0xf bank_mask:0xf
	v_mov_b32_dpp v213, v119 row_ror:2 row_mask:0xf bank_mask:0xf
	v_mov_b32_dpp v128, v118 row_ror:1 row_mask:0xf bank_mask:0xf
	v_mov_b32_dpp v212, v119 row_ror:1 row_mask:0xf bank_mask:0xf
	v_cndmask_b32_e32 v123, v213, v205, vcc
	v_cndmask_b32_e32 v122, v129, v204, vcc
	s_waitcnt lgkmcnt(0)
	v_pk_mul_f32 v[122:123], v[158:159], v[122:123]
	v_cndmask_b32_e64 v125, v212, v203, s[38:39]
	v_cndmask_b32_e64 v124, v128, v202, s[38:39]
	v_pk_fma_f32 v[122:123], v[150:151], v[124:125], v[122:123]
	v_mov_b32_dpp v211, v114 row_ror:2 row_mask:0xf bank_mask:0xf
	v_pk_fma_f32 v[118:119], v[118:119], v[146:147], v[122:123]
	v_mov_b32_dpp v225, v115 row_ror:2 row_mask:0xf bank_mask:0xf
	v_pk_add_f32 v[118:119], v[154:155], v[118:119]
	v_mov_b32_dpp v210, v114 row_ror:1 row_mask:0xf bank_mask:0xf
	v_mul_f32_e32 v122, 0xbfb8aa3b, v118
	v_mul_f32_e32 v123, 0xbfb8aa3b, v119
	v_exp_f32_e32 v122, v122
	v_exp_f32_e32 v123, v123
	v_mov_b32_dpp v224, v115 row_ror:1 row_mask:0xf bank_mask:0xf
	v_cndmask_b32_e32 v125, v225, v201, vcc
	v_cndmask_b32_e32 v124, v211, v200, vcc
	v_pk_mul_f32 v[124:125], v[142:143], v[124:125]
	v_cndmask_b32_e64 v127, v224, v197, s[38:39]
	v_cndmask_b32_e64 v126, v210, v196, s[38:39]
	v_mov_b32_dpp v227, v120 row_ror:2 row_mask:0xf bank_mask:0xf
	v_mov_b32_dpp v202, v121 row_ror:2 row_mask:0xf bank_mask:0xf
	v_add_f32_e32 v122, 1.0, v122
	v_pk_fma_f32 v[124:125], v[130:131], v[126:127], v[124:125]
	v_add_f32_e32 v123, 1.0, v123
	v_mov_b32_dpp v226, v120 row_ror:1 row_mask:0xf bank_mask:0xf
	v_mov_b32_dpp v230, v121 row_ror:1 row_mask:0xf bank_mask:0xf
	v_rcp_f32_e32 v122, v122
	v_pk_fma_f32 v[114:115], v[114:115], v[134:135], v[124:125]
	v_rcp_f32_e32 v123, v123
	v_cndmask_b32_e32 v125, v202, v199, vcc
	v_cndmask_b32_e32 v124, v227, v198, vcc
	v_pk_mul_f32 v[124:125], v[160:161], v[124:125]
	v_cndmask_b32_e64 v127, v230, v195, s[38:39]
	v_cndmask_b32_e64 v126, v226, v194, s[38:39]
	v_pk_fma_f32 v[124:125], v[152:153], v[126:127], v[124:125]
	v_pk_add_f32 v[114:115], v[138:139], v[114:115]
	v_pk_fma_f32 v[120:121], v[120:121], v[148:149], v[124:125]
	v_pk_mul_f32 v[118:119], v[118:119], v[122:123]
	v_pk_add_f32 v[120:121], v[156:157], v[120:121]
	v_pk_mul_f32 v[114:115], v[114:115], v[118:119]
	v_mul_f32_e32 v124, 0xbfb8aa3b, v120
	v_mul_f32_e32 v119, 0xbfb8aa3b, v121
	v_exp_f32_e32 v124, v124
	v_exp_f32_e32 v119, v119
	v_mov_b32_dpp v229, v116 row_ror:2 row_mask:0xf bank_mask:0xf
	v_mov_b32_dpp v204, v117 row_ror:2 row_mask:0xf bank_mask:0xf
	v_add_f32_e32 v118, 1.0, v124
	v_add_f32_e32 v119, 1.0, v119
	v_mov_b32_dpp v228, v116 row_ror:1 row_mask:0xf bank_mask:0xf
	v_mov_b32_dpp v203, v117 row_ror:1 row_mask:0xf bank_mask:0xf
	v_rcp_f32_e32 v118, v118
	v_cndmask_b32_e32 v123, v204, v193, vcc
	v_cndmask_b32_e32 v122, v229, v192, vcc
	v_rcp_f32_e32 v119, v119
	v_pk_mul_f32 v[122:123], v[144:145], v[122:123]
	v_cndmask_b32_e64 v125, v203, v191, s[38:39]
	v_cndmask_b32_e64 v124, v228, v190, s[38:39]
	v_pk_fma_f32 v[122:123], v[132:133], v[124:125], v[122:123]
	s_or_b32 s3, s63, 16
	v_pk_fma_f32 v[116:117], v[116:117], v[136:137], v[122:123]
	v_pk_mul_f32 v[118:119], v[120:121], v[118:119]
	v_pk_add_f32 v[116:117], v[140:141], v[116:117]
	s_mul_hi_i32 s5, s3, 0x1600
	s_mulk_i32 s3, 0x1600
	v_pk_mul_f32 v[116:117], v[116:117], v[118:119]
	s_add_u32 s4, s79, s3
	v_cvt_pk_bf16_f32 v117, v116, v117
	v_cvt_pk_bf16_f32 v116, v114, v115
	s_addc_u32 s5, s84, s5
	v_lshlrev_b64 v[114:115], 1, v[80:81]
	v_lshl_add_u64 v[118:119], s[4:5], 0, v[114:115]
	global_store_dwordx2 v[118:119], v[116:117], off
	v_mov_b32_dpp v122, v110 row_ror:2 row_mask:0xf bank_mask:0xf
	v_mov_b32_dpp v126, v111 row_ror:2 row_mask:0xf bank_mask:0xf
	v_mov_b32_dpp v80, v110 row_ror:1 row_mask:0xf bank_mask:0xf
	v_mov_b32_dpp v125, v111 row_ror:1 row_mask:0xf bank_mask:0xf
	v_cndmask_b32_e32 v117, v126, v213, vcc
	v_cndmask_b32_e32 v116, v122, v129, vcc
	v_pk_mul_f32 v[116:117], v[158:159], v[116:117]
	v_cndmask_b32_e64 v119, v125, v212, s[38:39]
	v_cndmask_b32_e64 v118, v80, v128, s[38:39]
	v_pk_fma_f32 v[116:117], v[150:151], v[118:119], v[116:117]
	v_mov_b32_dpp v124, v106 row_ror:2 row_mask:0xf bank_mask:0xf
	v_pk_fma_f32 v[110:111], v[110:111], v[146:147], v[116:117]
	v_mov_b32_dpp v190, v107 row_ror:2 row_mask:0xf bank_mask:0xf
	v_pk_add_f32 v[110:111], v[154:155], v[110:111]
	v_mov_b32_dpp v123, v106 row_ror:1 row_mask:0xf bank_mask:0xf
	v_mul_f32_e32 v116, 0xbfb8aa3b, v110
	v_mul_f32_e32 v117, 0xbfb8aa3b, v111
	v_exp_f32_e32 v116, v116
	v_exp_f32_e32 v117, v117
	v_mov_b32_dpp v127, v107 row_ror:1 row_mask:0xf bank_mask:0xf
	v_cndmask_b32_e32 v119, v190, v225, vcc
	v_add_f32_e32 v116, 1.0, v116
	v_add_f32_e32 v117, 1.0, v117
	v_rcp_f32_e32 v116, v116
	v_cndmask_b32_e32 v118, v124, v211, vcc
	v_rcp_f32_e32 v117, v117
	v_pk_mul_f32 v[118:119], v[142:143], v[118:119]
	v_cndmask_b32_e64 v121, v127, v224, s[38:39]
	v_cndmask_b32_e64 v120, v123, v210, s[38:39]
	v_pk_fma_f32 v[118:119], v[130:131], v[120:121], v[118:119]
	v_mov_b32_dpp v192, v112 row_ror:2 row_mask:0xf bank_mask:0xf
	v_pk_fma_f32 v[106:107], v[106:107], v[134:135], v[118:119]
	v_mov_b32_dpp v196, v113 row_ror:2 row_mask:0xf bank_mask:0xf
	v_pk_add_f32 v[106:107], v[138:139], v[106:107]
	v_pk_mul_f32 v[110:111], v[110:111], v[116:117]
	v_mov_b32_dpp v191, v112 row_ror:1 row_mask:0xf bank_mask:0xf
	v_mov_b32_dpp v195, v113 row_ror:1 row_mask:0xf bank_mask:0xf
	v_pk_mul_f32 v[106:107], v[106:107], v[110:111]
	v_cndmask_b32_e32 v111, v196, v202, vcc
; __device__ __forceinline__ unsigned cvt_pk_bf16(float lo, float hi) { f32x2_cv v = {lo, hi}; bf16x2_cv b = __builtin_convertvector(v, bf16x2_cv); return __builtin_bit_cast(unsigned, b); }
;     __device__ __forceinline__ void operator()(const f32x4 (&acc)[2][2][4][2], const Unit& u, int wr, int wc, int fr_, int fq_) const {
;     ...
;             for (int n = 0; n < 2; ++n) {
;                 int jl = jbase + 4 * n; asm volatile("" : "+v"(jl) :: "memory");
;                 const unsigned j = (unsigned)jl;
;                 const f32x4 wg0 = *(const f32x4*)(cw + j), wg1 = *(const f32x4*)(cw + 5632 + j), wg2 = *(const f32x4*)(cw + 2 * 5632 + j), bg = *(const f32x4*)(cb + j);
;                 const f32x4 wv0 = *(const f32x4*)(cw + 2816 + j), wv1 = *(const f32x4*)(cw + 5632 + 2816 + j), wv2 = *(const f32x4*)(cw + 2 * 5632 + 2816 + j), bv = *(const f32x4*)(cb + 2816 + j);
;                 const unsigned loff = (unsigned)fr * 2816u + j;
;                 const bool c1 = fr == 0, c2 = fr < 2;
;                 f32x4 g1p = (f32x4){0.f, 0.f, 0.f, 0.f}, g2p = g1p, v1p = g1p, v2p = g1p;
; #pragma unroll
;                 for (int m = 0; m < 4; ++m) {
;                     const f32x4 xg = acc[ai][0][m][n], xv = acc[ai][1][m][n];
;                     f32x4 g1, g2, v1, v2;
; #pragma unroll
;                     for (int i = 0; i < 4; ++i) { g1[i] = dpp_ror1(xg[i]); g2[i] = dpp_ror2(xg[i]); v1[i] = dpp_ror1(xv[i]); v2[i] = dpp_ror2(xv[i]); }
;                     f32x4 pg1, pg2, pv1, pv2;
; #pragma unroll
;                     for (int i = 0; i < 4; ++i) { pg1[i] = c1 ? g1p[i] : g1[i]; pg2[i] = c2 ? g2p[i] : g2[i]; pv1[i] = c1 ? v1p[i] : v1[i]; pv2[i] = c2 ? v2p[i] : v2[i]; }
;                     const f32x4 G = wg0 * pg2 + wg1 * pg1 + wg2 * xg + bg;
;                     const f32x4 V = wv0 * pv2 + wv1 * pv1 + wv2 * xv + bv;
;                     f32x4 r;
; #pragma unroll
;                     for (int i = 0; i < 4; ++i) r[i] = G[i] * __builtin_amdgcn_rcpf(1.0f + __builtin_amdgcn_exp2f(-1.4426950408889634f * G[i])) * V[i];
;                     u32x2 w; w.x = cvt_pk_bf16(r[0], r[1]); w.y = cvt_pk_bf16(r[2], r[3]);
;                     if (m > 0 || !c2) *(u32x2*)(ACT + (size_t)(rowu + ai * HALF + m * 16) * 2816 + loff) = w;
;                     g1p = g1; g2p = g2; v1p = v1; v2p = v2;
	v_cndmask_b32_e32 v110, v192, v227, vcc
	v_pk_mul_f32 v[110:111], v[160:161], v[110:111]
	v_cndmask_b32_e64 v117, v195, v230, s[38:39]
	v_cndmask_b32_e64 v116, v191, v226, s[38:39]
	v_pk_fma_f32 v[110:111], v[152:153], v[116:117], v[110:111]
	v_mov_b32_dpp v194, v108 row_ror:2 row_mask:0xf bank_mask:0xf
	v_pk_fma_f32 v[110:111], v[112:113], v[148:149], v[110:111]
	v_mov_b32_dpp v198, v109 row_ror:2 row_mask:0xf bank_mask:0xf
	v_pk_add_f32 v[110:111], v[156:157], v[110:111]
	v_mov_b32_dpp v193, v108 row_ror:1 row_mask:0xf bank_mask:0xf
	v_mul_f32_e32 v112, 0xbfb8aa3b, v110
	v_mul_f32_e32 v113, 0xbfb8aa3b, v111
	v_exp_f32_e32 v112, v112
	v_exp_f32_e32 v113, v113
	v_mov_b32_dpp v197, v109 row_ror:1 row_mask:0xf bank_mask:0xf
	v_cndmask_b32_e32 v117, v198, v204, vcc
	v_add_f32_e32 v112, 1.0, v112
	v_add_f32_e32 v113, 1.0, v113
	v_rcp_f32_e32 v112, v112
	v_cndmask_b32_e32 v116, v194, v229, vcc
	v_rcp_f32_e32 v113, v113
	v_pk_mul_f32 v[116:117], v[144:145], v[116:117]
	v_cndmask_b32_e64 v119, v197, v203, s[38:39]
	v_cndmask_b32_e64 v118, v193, v228, s[38:39]
	v_pk_fma_f32 v[116:117], v[132:133], v[118:119], v[116:117]
	s_or_b32 s3, s63, 32
	v_pk_fma_f32 v[108:109], v[108:109], v[136:137], v[116:117]
	s_mul_hi_i32 s13, s3, 0x1600
	s_mulk_i32 s3, 0x1600
	v_pk_add_f32 v[108:109], v[140:141], v[108:109]
	v_pk_mul_f32 v[110:111], v[110:111], v[112:113]
	s_add_u32 s12, s79, s3
	v_pk_mul_f32 v[108:109], v[108:109], v[110:111]
	s_addc_u32 s13, s84, s13
	v_cvt_pk_bf16_f32 v109, v108, v109
	v_cvt_pk_bf16_f32 v108, v106, v107
	v_lshl_add_u64 v[106:107], s[12:13], 0, v[114:115]
	global_store_dwordx2 v[106:107], v[108:109], off
	s_nop 0
	v_mov_b32_dpp v106, v102 row_ror:2 row_mask:0xf bank_mask:0xf
	v_mov_b32_dpp v107, v103 row_ror:2 row_mask:0xf bank_mask:0xf
	v_mov_b32_dpp v108, v102 row_ror:1 row_mask:0xf bank_mask:0xf
	v_mov_b32_dpp v109, v103 row_ror:1 row_mask:0xf bank_mask:0xf
	v_cndmask_b32_e32 v107, v107, v126, vcc
	v_cndmask_b32_e32 v106, v106, v122, vcc
	v_pk_mul_f32 v[106:107], v[158:159], v[106:107]
	v_cndmask_b32_e64 v109, v109, v125, s[38:39]
	v_cndmask_b32_e64 v108, v108, v80, s[38:39]
	v_pk_fma_f32 v[106:107], v[150:151], v[108:109], v[106:107]
	v_mov_b32_dpp v111, v98 row_ror:2 row_mask:0xf bank_mask:0xf
	v_pk_fma_f32 v[102:103], v[102:103], v[146:147], v[106:107]
	v_mov_b32_dpp v113, v99 row_ror:2 row_mask:0xf bank_mask:0xf
	v_pk_add_f32 v[102:103], v[154:155], v[102:103]
	v_mov_b32_dpp v110, v98 row_ror:1 row_mask:0xf bank_mask:0xf
	v_mul_f32_e32 v80, 0xbfb8aa3b, v102
	v_exp_f32_e32 v80, v80
	v_mov_b32_dpp v112, v99 row_ror:1 row_mask:0xf bank_mask:0xf
	v_cndmask_b32_e32 v109, v113, v190, vcc
	v_cndmask_b32_e32 v108, v111, v124, vcc
	v_add_f32_e32 v80, 1.0, v80
	v_pk_mul_f32 v[108:109], v[142:143], v[108:109]
	v_cndmask_b32_e64 v111, v112, v127, s[38:39]
	v_cndmask_b32_e64 v110, v110, v123, s[38:39]
	v_mov_b32_dpp v117, v104 row_ror:2 row_mask:0xf bank_mask:0xf
	v_mov_b32_dpp v121, v105 row_ror:2 row_mask:0xf bank_mask:0xf
	v_rcp_f32_e32 v106, v80
	v_mul_f32_e32 v80, 0xbfb8aa3b, v103
	v_pk_fma_f32 v[108:109], v[130:131], v[110:111], v[108:109]
	v_mov_b32_dpp v116, v104 row_ror:1 row_mask:0xf bank_mask:0xf
	v_mov_b32_dpp v120, v105 row_ror:1 row_mask:0xf bank_mask:0xf
	v_exp_f32_e32 v80, v80
	v_pk_fma_f32 v[98:99], v[98:99], v[134:135], v[108:109]
	v_cndmask_b32_e32 v109, v121, v196, vcc
	v_cndmask_b32_e32 v108, v117, v192, vcc
	v_pk_mul_f32 v[108:109], v[160:161], v[108:109]
	v_cndmask_b32_e64 v111, v120, v195, s[38:39]
	v_cndmask_b32_e64 v110, v116, v191, s[38:39]
	v_pk_fma_f32 v[108:109], v[152:153], v[110:111], v[108:109]
	v_add_f32_e32 v80, 1.0, v80
	v_pk_fma_f32 v[104:105], v[104:105], v[148:149], v[108:109]
	v_rcp_f32_e32 v107, v80
	v_pk_add_f32 v[104:105], v[156:157], v[104:105]
	v_pk_add_f32 v[98:99], v[138:139], v[98:99]
	v_mul_f32_e32 v80, 0xbfb8aa3b, v104
	v_exp_f32_e32 v80, v80
	v_pk_mul_f32 v[102:103], v[102:103], v[106:107]
	v_mov_b32_dpp v119, v100 row_ror:2 row_mask:0xf bank_mask:0xf
	v_pk_mul_f32 v[98:99], v[98:99], v[102:103]
	v_add_f32_e32 v80, 1.0, v80
	v_rcp_f32_e32 v102, v80
	v_mul_f32_e32 v80, 0xbfb8aa3b, v105
	v_exp_f32_e32 v80, v80
	v_mov_b32_dpp v125, v101 row_ror:2 row_mask:0xf bank_mask:0xf
	v_mov_b32_dpp v118, v100 row_ror:1 row_mask:0xf bank_mask:0xf
	v_mov_b32_dpp v122, v101 row_ror:1 row_mask:0xf bank_mask:0xf
	v_add_f32_e32 v80, 1.0, v80
	v_cndmask_b32_e32 v107, v125, v198, vcc
	v_cndmask_b32_e32 v106, v119, v194, vcc
	v_rcp_f32_e32 v103, v80
	v_pk_mul_f32 v[106:107], v[144:145], v[106:107]
	v_cndmask_b32_e64 v109, v122, v197, s[38:39]
	v_cndmask_b32_e64 v108, v118, v193, s[38:39]
	v_pk_fma_f32 v[106:107], v[132:133], v[108:109], v[106:107]
	s_or_b32 s3, s63, 48
	v_pk_fma_f32 v[100:101], v[100:101], v[136:137], v[106:107]
	s_mul_hi_i32 s21, s3, 0x1600
	s_mulk_i32 s3, 0x1600
	v_pk_add_f32 v[100:101], v[140:141], v[100:101]
	v_pk_mul_f32 v[102:103], v[104:105], v[102:103]
	s_add_u32 s20, s79, s3
	v_pk_mul_f32 v[100:101], v[100:101], v[102:103]
	s_addc_u32 s21, s84, s21
	v_cvt_pk_bf16_f32 v101, v100, v101
	v_cvt_pk_bf16_f32 v100, v98, v99
	v_lshl_add_u64 v[98:99], s[20:21], 0, v[114:115]
	global_store_dwordx2 v[98:99], v[100:101], off
	v_or_b32_e32 v130, 4, v188
	v_mov_b32_e32 v80, v130
	v_mov_b32_dpp v144, v94 row_ror:1 row_mask:0xf bank_mask:0xf
	v_lshlrev_b32_e32 v106, 2, v80
	v_and_b32_e32 v106, 0x1ff, v106
	v_add_u32_e32 v106, s101, v106
	ds_read_b128 v[126:129], v106 offset:0
	ds_read_b128 v[118:121], v106 offset:512
	ds_read_b128 v[114:117], v106 offset:1024
	ds_read_b128 v[122:125], v106 offset:1536
	ds_read_b128 v[110:113], v106 offset:2048
	s_nop 0
	ds_read_b128 v[98:101], v106 offset:2560
	v_add_u32_e32 v80, v80, v222
	ds_read_b128 v[102:105], v106 offset:3072
	v_mov_b32_dpp v146, v94 row_ror:2 row_mask:0xf bank_mask:0xf
	ds_read_b128 v[106:109], v106 offset:3584
	v_mov_b32_dpp v138, v90 row_ror:1 row_mask:0xf bank_mask:0xf
	v_mov_b32_dpp v142, v90 row_ror:2 row_mask:0xf bank_mask:0xf
	v_mov_b32_dpp v145, v95 row_ror:1 row_mask:0xf bank_mask:0xf
	v_mov_b32_dpp v147, v95 row_ror:2 row_mask:0xf bank_mask:0xf
	v_mov_b32_dpp v139, v91 row_ror:1 row_mask:0xf bank_mask:0xf
	v_mov_b32_dpp v143, v91 row_ror:2 row_mask:0xf bank_mask:0xf
	v_mov_b32_dpp v136, v96 row_ror:1 row_mask:0xf bank_mask:0xf
	v_mov_b32_dpp v140, v96 row_ror:2 row_mask:0xf bank_mask:0xf
	v_mov_b32_dpp v132, v92 row_ror:1 row_mask:0xf bank_mask:0xf
	v_mov_b32_dpp v134, v92 row_ror:2 row_mask:0xf bank_mask:0xf
	v_mov_b32_dpp v137, v97 row_ror:1 row_mask:0xf bank_mask:0xf
	v_mov_b32_dpp v141, v97 row_ror:2 row_mask:0xf bank_mask:0xf
	v_mov_b32_dpp v133, v93 row_ror:1 row_mask:0xf bank_mask:0xf
	v_mov_b32_dpp v135, v93 row_ror:2 row_mask:0xf bank_mask:0xf
	s_and_saveexec_b64 s[70:71], s[40:41]
	s_xor_b64 s[70:71], exec, s[70:71]
	s_cbranch_execz .LBB0_570
; __device__ __forceinline__ unsigned cvt_pk_bf16(float lo, float hi) { f32x2_cv v = {lo, hi}; bf16x2_cv b = __builtin_convertvector(v, bf16x2_cv); return __builtin_bit_cast(unsigned, b); }
; __device__ __forceinline__ float dpp_ror1(float v) { return __builtin_bit_cast(float, __builtin_amdgcn_mov_dpp(__builtin_bit_cast(int, v), 0x121, 0xf, 0xf, false)); }
; __device__ __forceinline__ float dpp_ror2(float v) { return __builtin_bit_cast(float, __builtin_amdgcn_mov_dpp(__builtin_bit_cast(int, v), 0x122, 0xf, 0xf, false)); }
;     __device__ __forceinline__ void operator()(const f32x4 (&acc)[2][2][4][2], const Unit& u, int wr, int wc, int fr_, int fq_) const {
;     ...
;                 for (int m = 0; m < 4; ++m) {
;                     const f32x4 xg = acc[ai][0][m][n], xv = acc[ai][1][m][n];
;                     f32x4 g1, g2, v1, v2;
; #pragma unroll
;                     for (int i = 0; i < 4; ++i) { g1[i] = dpp_ror1(xg[i]); g2[i] = dpp_ror2(xg[i]); v1[i] = dpp_ror1(xv[i]); v2[i] = dpp_ror2(xv[i]); }
;                     f32x4 pg1, pg2, pv1, pv2;
; #pragma unroll
;                     for (int i = 0; i < 4; ++i) { pg1[i] = c1 ? g1p[i] : g1[i]; pg2[i] = c2 ? g2p[i] : g2[i]; pv1[i] = c1 ? v1p[i] : v1[i]; pv2[i] = c2 ? v2p[i] : v2[i]; }
;                     const f32x4 G = wg0 * pg2 + wg1 * pg1 + wg2 * xg + bg;
;                     const f32x4 V = wv0 * pv2 + wv1 * pv1 + wv2 * xv + bv;
;                     f32x4 r;
; #pragma unroll
;                     for (int i = 0; i < 4; ++i) r[i] = G[i] * __builtin_amdgcn_rcpf(1.0f + __builtin_amdgcn_exp2f(-1.4426950408889634f * G[i])) * V[i];
;                     u32x2 w; w.x = cvt_pk_bf16(r[0], r[1]); w.y = cvt_pk_bf16(r[2], r[3]);
;                     if (m > 0 || !c2) *(u32x2*)(ACT + (size_t)(rowu + ai * HALF + m * 16) * 2816 + loff) = w;
;                     g1p = g1; g2p = g2; v1p = v1; v2p = v2;
	s_waitcnt lgkmcnt(0)
	v_pk_mul_f32 v[148:149], v[126:127], v[146:147]
	v_pk_mul_f32 v[150:151], v[110:111], v[142:143]
	v_pk_fma_f32 v[148:149], v[118:119], v[144:145], v[148:149]
	v_pk_fma_f32 v[150:151], v[98:99], v[138:139], v[150:151]
	v_pk_fma_f32 v[94:95], v[94:95], v[114:115], v[148:149]
	v_pk_fma_f32 v[90:91], v[90:91], v[102:103], v[150:151]
	v_pk_add_f32 v[94:95], v[122:123], v[94:95]
	v_pk_add_f32 v[90:91], v[106:107], v[90:91]
	v_mul_f32_e32 v131, 0xbfb8aa3b, v94
	v_exp_f32_e32 v131, v131
	s_mul_hi_i32 s3, s63, 0x1600
	s_add_u32 s80, s79, s65
	s_addc_u32 s81, s84, s3
	v_add_f32_e32 v131, 1.0, v131
	v_rcp_f32_e32 v148, v131
	v_mul_f32_e32 v131, 0xbfb8aa3b, v95
	v_exp_f32_e32 v131, v131
	s_nop 0
	v_add_f32_e32 v131, 1.0, v131
	v_rcp_f32_e32 v149, v131
	s_nop 0
	v_pk_mul_f32 v[94:95], v[94:95], v[148:149]
	s_nop 0
	v_pk_mul_f32 v[90:91], v[90:91], v[94:95]
	v_pk_mul_f32 v[94:95], v[128:129], v[140:141]
	v_pk_mul_f32 v[148:149], v[112:113], v[134:135]
	v_pk_fma_f32 v[94:95], v[120:121], v[136:137], v[94:95]
	v_pk_fma_f32 v[148:149], v[100:101], v[132:133], v[148:149]
	v_pk_fma_f32 v[94:95], v[96:97], v[116:117], v[94:95]
	v_pk_fma_f32 v[92:93], v[92:93], v[104:105], v[148:149]
	v_pk_add_f32 v[94:95], v[124:125], v[94:95]
	v_pk_add_f32 v[92:93], v[108:109], v[92:93]
	v_mul_f32_e32 v96, 0xbfb8aa3b, v94
	v_mul_f32_e32 v97, 0xbfb8aa3b, v95
	v_exp_f32_e32 v96, v96
	v_exp_f32_e32 v97, v97
	v_add_f32_e32 v96, 1.0, v96
	v_add_f32_e32 v97, 1.0, v97
	v_rcp_f32_e32 v96, v96
	v_rcp_f32_e32 v97, v97
	s_nop 0
	v_pk_mul_f32 v[94:95], v[94:95], v[96:97]
	s_nop 0
	v_pk_mul_f32 v[92:93], v[92:93], v[94:95]
	s_nop 0
	v_cvt_pk_bf16_f32 v93, v92, v93
	v_cvt_pk_bf16_f32 v92, v90, v91
	v_lshl_add_u64 v[90:91], v[80:81], 1, s[80:81]
	global_store_dwordx2 v[90:91], v[92:93], off
.LBB0_570:
	s_andn2_saveexec_b64 s[70:71], s[70:71]
	s_or_b64 exec, exec, s[70:71]
	v_mov_b32_dpp v97, v86 row_ror:2 row_mask:0xf bank_mask:0xf
	v_mov_b32_dpp v150, v87 row_ror:2 row_mask:0xf bank_mask:0xf
	v_mov_b32_dpp v96, v86 row_ror:1 row_mask:0xf bank_mask:0xf
	v_mov_b32_dpp v149, v87 row_ror:1 row_mask:0xf bank_mask:0xf
	v_cndmask_b32_e32 v91, v150, v147, vcc
	v_cndmask_b32_e32 v90, v97, v146, vcc
	s_waitcnt lgkmcnt(0)
	v_pk_mul_f32 v[90:91], v[126:127], v[90:91]
	v_cndmask_b32_e64 v93, v149, v145, s[38:39]
	v_cndmask_b32_e64 v92, v96, v144, s[38:39]
	v_pk_fma_f32 v[90:91], v[118:119], v[92:93], v[90:91]
	v_mov_b32_dpp v148, v82 row_ror:2 row_mask:0xf bank_mask:0xf
	v_pk_fma_f32 v[86:87], v[86:87], v[114:115], v[90:91]
	v_mov_b32_dpp v152, v83 row_ror:2 row_mask:0xf bank_mask:0xf
	v_pk_add_f32 v[86:87], v[122:123], v[86:87]
	v_mov_b32_dpp v131, v82 row_ror:1 row_mask:0xf bank_mask:0xf
	v_mul_f32_e32 v90, 0xbfb8aa3b, v86
	v_mul_f32_e32 v91, 0xbfb8aa3b, v87
	v_exp_f32_e32 v90, v90
	v_exp_f32_e32 v91, v91
	v_mov_b32_dpp v151, v83 row_ror:1 row_mask:0xf bank_mask:0xf
	v_cndmask_b32_e32 v93, v152, v143, vcc
	v_cndmask_b32_e32 v92, v148, v142, vcc
	v_pk_mul_f32 v[92:93], v[110:111], v[92:93]
	v_cndmask_b32_e64 v95, v151, v139, s[38:39]
	v_cndmask_b32_e64 v94, v131, v138, s[38:39]
	v_mov_b32_dpp v154, v88 row_ror:2 row_mask:0xf bank_mask:0xf
	v_mov_b32_dpp v144, v89 row_ror:2 row_mask:0xf bank_mask:0xf
	v_add_f32_e32 v90, 1.0, v90
	v_pk_fma_f32 v[92:93], v[98:99], v[94:95], v[92:93]
	v_add_f32_e32 v91, 1.0, v91
	v_mov_b32_dpp v153, v88 row_ror:1 row_mask:0xf bank_mask:0xf
	v_mov_b32_dpp v157, v89 row_ror:1 row_mask:0xf bank_mask:0xf
	v_rcp_f32_e32 v90, v90
	v_pk_fma_f32 v[82:83], v[82:83], v[102:103], v[92:93]
	v_rcp_f32_e32 v91, v91
	v_cndmask_b32_e32 v93, v144, v141, vcc
	v_cndmask_b32_e32 v92, v154, v140, vcc
	v_pk_mul_f32 v[92:93], v[128:129], v[92:93]
	v_cndmask_b32_e64 v95, v157, v137, s[38:39]
	v_cndmask_b32_e64 v94, v153, v136, s[38:39]
	v_pk_fma_f32 v[92:93], v[120:121], v[94:95], v[92:93]
	v_pk_add_f32 v[82:83], v[106:107], v[82:83]
	v_pk_fma_f32 v[88:89], v[88:89], v[116:117], v[92:93]
	v_pk_mul_f32 v[86:87], v[86:87], v[90:91]
	v_pk_add_f32 v[88:89], v[124:125], v[88:89]
	v_pk_mul_f32 v[82:83], v[82:83], v[86:87]
	v_mul_f32_e32 v92, 0xbfb8aa3b, v88
	v_mul_f32_e32 v87, 0xbfb8aa3b, v89
	v_exp_f32_e32 v92, v92
	v_exp_f32_e32 v87, v87
	v_mov_b32_dpp v156, v84 row_ror:2 row_mask:0xf bank_mask:0xf
	v_mov_b32_dpp v146, v85 row_ror:2 row_mask:0xf bank_mask:0xf
	v_add_f32_e32 v86, 1.0, v92
	v_add_f32_e32 v87, 1.0, v87
	v_mov_b32_dpp v155, v84 row_ror:1 row_mask:0xf bank_mask:0xf
	v_mov_b32_dpp v145, v85 row_ror:1 row_mask:0xf bank_mask:0xf
	v_rcp_f32_e32 v86, v86
	v_cndmask_b32_e32 v91, v146, v135, vcc
	v_cndmask_b32_e32 v90, v156, v134, vcc
	v_rcp_f32_e32 v87, v87
	v_pk_mul_f32 v[90:91], v[112:113], v[90:91]
	v_cndmask_b32_e64 v93, v145, v133, s[38:39]
	v_cndmask_b32_e64 v92, v155, v132, s[38:39]
	v_pk_fma_f32 v[90:91], v[100:101], v[92:93], v[90:91]
	v_pk_mul_f32 v[86:87], v[88:89], v[86:87]
	v_pk_fma_f32 v[84:85], v[84:85], v[104:105], v[90:91]
	s_nop 0
	v_pk_add_f32 v[84:85], v[108:109], v[84:85]
	s_nop 0
	v_pk_mul_f32 v[84:85], v[84:85], v[86:87]
	s_nop 0
	v_cvt_pk_bf16_f32 v85, v84, v85
	v_cvt_pk_bf16_f32 v84, v82, v83
	v_lshlrev_b64 v[82:83], 1, v[80:81]
	v_lshl_add_u64 v[86:87], s[4:5], 0, v[82:83]
	global_store_dwordx2 v[86:87], v[84:85], off
	v_mov_b32_dpp v90, v76 row_ror:2 row_mask:0xf bank_mask:0xf
	v_mov_b32_dpp v94, v77 row_ror:2 row_mask:0xf bank_mask:0xf
	v_mov_b32_dpp v80, v76 row_ror:1 row_mask:0xf bank_mask:0xf
	v_mov_b32_dpp v93, v77 row_ror:1 row_mask:0xf bank_mask:0xf
	v_cndmask_b32_e32 v85, v94, v150, vcc
	v_cndmask_b32_e32 v84, v90, v97, vcc
	v_pk_mul_f32 v[84:85], v[126:127], v[84:85]
	v_cndmask_b32_e64 v87, v93, v149, s[38:39]
; __device__ __forceinline__ unsigned cvt_pk_bf16(float lo, float hi) { f32x2_cv v = {lo, hi}; bf16x2_cv b = __builtin_convertvector(v, bf16x2_cv); return __builtin_bit_cast(unsigned, b); }
; __device__ __forceinline__ float dpp_ror1(float v) { return __builtin_bit_cast(float, __builtin_amdgcn_mov_dpp(__builtin_bit_cast(int, v), 0x121, 0xf, 0xf, false)); }
;     __device__ __forceinline__ void operator()(const f32x4 (&acc)[2][2][4][2], const Unit& u, int wr, int wc, int fr_, int fq_) const {
;     ...
;             for (int mm = 0; mm < 2; ++mm) { const int m = mm * 3;
;                 const bool is_edge = mm == 0 ? (fr < 2) : (fr >= 14);
;                 if (is_edge) { const unsigned e = (unsigned)(mm == 0 ? fr : fr - 12);
;                     bf16_t* eb = edge + (size_t)grp * 4 * 5632;
; #pragma unroll
;                     for (int bj = 0; bj < 2; ++bj) { const f32x4 v0 = acc[ai][bj][m][0], v1 = acc[ai][bj][m][1];
;                         u32x4 w; w.x = cvt_pk_bf16(v0[0], v0[1]); w.y = cvt_pk_bf16(v0[2], v0[3]); w.z = cvt_pk_bf16(v1[0], v1[1]); w.w = cvt_pk_bf16(v1[2], v1[3]);
;                         *(u32x4*)(eb + (e * 5632u + ecol + (unsigned)(bj * HALF))) = w; } } }
;     ...
;                 for (int m = 0; m < 4; ++m) {
;                     const f32x4 xg = acc[ai][0][m][n], xv = acc[ai][1][m][n];
;                     f32x4 g1, g2, v1, v2;
; #pragma unroll
;                     for (int i = 0; i < 4; ++i) { g1[i] = dpp_ror1(xg[i]); g2[i] = dpp_ror2(xg[i]); v1[i] = dpp_ror1(xv[i]); v2[i] = dpp_ror2(xv[i]); }
;                     f32x4 pg1, pg2, pv1, pv2;
; #pragma unroll
;                     for (int i = 0; i < 4; ++i) { pg1[i] = c1 ? g1p[i] : g1[i]; pg2[i] = c2 ? g2p[i] : g2[i]; pv1[i] = c1 ? v1p[i] : v1[i]; pv2[i] = c2 ? v2p[i] : v2[i]; }
;                     const f32x4 G = wg0 * pg2 + wg1 * pg1 + wg2 * xg + bg;
;                     const f32x4 V = wv0 * pv2 + wv1 * pv1 + wv2 * xv + bv;
;                     f32x4 r;
; #pragma unroll
;                     for (int i = 0; i < 4; ++i) r[i] = G[i] * __builtin_amdgcn_rcpf(1.0f + __builtin_amdgcn_exp2f(-1.4426950408889634f * G[i])) * V[i];
;                     u32x2 w; w.x = cvt_pk_bf16(r[0], r[1]); w.y = cvt_pk_bf16(r[2], r[3]);
;                     if (m > 0 || !c2) *(u32x2*)(ACT + (size_t)(rowu + ai * HALF + m * 16) * 2816 + loff) = w;
;                     g1p = g1; g2p = g2; v1p = v1; v2p = v2;
	v_cndmask_b32_e64 v86, v80, v96, s[38:39]
	v_pk_fma_f32 v[84:85], v[118:119], v[86:87], v[84:85]
	v_mov_b32_dpp v92, v72 row_ror:2 row_mask:0xf bank_mask:0xf
	v_pk_fma_f32 v[76:77], v[76:77], v[114:115], v[84:85]
	v_mov_b32_dpp v132, v73 row_ror:2 row_mask:0xf bank_mask:0xf
	v_pk_add_f32 v[76:77], v[122:123], v[76:77]
	v_mov_b32_dpp v91, v72 row_ror:1 row_mask:0xf bank_mask:0xf
	v_mul_f32_e32 v84, 0xbfb8aa3b, v76
	v_mul_f32_e32 v85, 0xbfb8aa3b, v77
	v_exp_f32_e32 v84, v84
	v_exp_f32_e32 v85, v85
	v_mov_b32_dpp v95, v73 row_ror:1 row_mask:0xf bank_mask:0xf
	v_cndmask_b32_e32 v87, v132, v152, vcc
	v_add_f32_e32 v84, 1.0, v84
	v_add_f32_e32 v85, 1.0, v85
	v_rcp_f32_e32 v84, v84
	v_cndmask_b32_e32 v86, v92, v148, vcc
	v_rcp_f32_e32 v85, v85
	v_pk_mul_f32 v[86:87], v[110:111], v[86:87]
	v_cndmask_b32_e64 v89, v95, v151, s[38:39]
	v_cndmask_b32_e64 v88, v91, v131, s[38:39]
	v_pk_fma_f32 v[86:87], v[98:99], v[88:89], v[86:87]
	v_mov_b32_dpp v134, v78 row_ror:2 row_mask:0xf bank_mask:0xf
	v_pk_fma_f32 v[72:73], v[72:73], v[102:103], v[86:87]
	v_mov_b32_dpp v138, v79 row_ror:2 row_mask:0xf bank_mask:0xf
	v_pk_add_f32 v[72:73], v[106:107], v[72:73]
	v_pk_mul_f32 v[76:77], v[76:77], v[84:85]
	v_mov_b32_dpp v133, v78 row_ror:1 row_mask:0xf bank_mask:0xf
	v_mov_b32_dpp v137, v79 row_ror:1 row_mask:0xf bank_mask:0xf
	v_pk_mul_f32 v[72:73], v[72:73], v[76:77]
	v_cndmask_b32_e32 v77, v138, v144, vcc
	v_cndmask_b32_e32 v76, v134, v154, vcc
	v_pk_mul_f32 v[76:77], v[128:129], v[76:77]
	v_cndmask_b32_e64 v85, v137, v157, s[38:39]
	v_cndmask_b32_e64 v84, v133, v153, s[38:39]
	v_pk_fma_f32 v[76:77], v[120:121], v[84:85], v[76:77]
	v_mov_b32_dpp v136, v74 row_ror:2 row_mask:0xf bank_mask:0xf
	v_pk_fma_f32 v[76:77], v[78:79], v[116:117], v[76:77]
	v_mov_b32_dpp v140, v75 row_ror:2 row_mask:0xf bank_mask:0xf
	v_pk_add_f32 v[76:77], v[124:125], v[76:77]
	v_mov_b32_dpp v135, v74 row_ror:1 row_mask:0xf bank_mask:0xf
	v_mul_f32_e32 v78, 0xbfb8aa3b, v76
	v_mul_f32_e32 v79, 0xbfb8aa3b, v77
	v_exp_f32_e32 v78, v78
	v_exp_f32_e32 v79, v79
	v_mov_b32_dpp v139, v75 row_ror:1 row_mask:0xf bank_mask:0xf
	v_cndmask_b32_e32 v85, v140, v146, vcc
	v_add_f32_e32 v78, 1.0, v78
	v_add_f32_e32 v79, 1.0, v79
	v_rcp_f32_e32 v78, v78
	v_cndmask_b32_e32 v84, v136, v156, vcc
	v_rcp_f32_e32 v79, v79
	v_pk_mul_f32 v[84:85], v[112:113], v[84:85]
	v_cndmask_b32_e64 v87, v139, v145, s[38:39]
	v_cndmask_b32_e64 v86, v135, v155, s[38:39]
	v_pk_fma_f32 v[84:85], v[100:101], v[86:87], v[84:85]
	v_pk_mul_f32 v[76:77], v[76:77], v[78:79]
	v_pk_fma_f32 v[74:75], v[74:75], v[104:105], v[84:85]
	s_nop 0
	v_pk_add_f32 v[74:75], v[108:109], v[74:75]
	s_nop 0
	v_pk_mul_f32 v[74:75], v[74:75], v[76:77]
	s_nop 0
	v_cvt_pk_bf16_f32 v75, v74, v75
	v_cvt_pk_bf16_f32 v74, v72, v73
	v_lshl_add_u64 v[72:73], s[12:13], 0, v[82:83]
	global_store_dwordx2 v[72:73], v[74:75], off
	s_nop 0
	v_mov_b32_dpp v72, v68 row_ror:2 row_mask:0xf bank_mask:0xf
	v_mov_b32_dpp v73, v69 row_ror:2 row_mask:0xf bank_mask:0xf
	v_mov_b32_dpp v74, v68 row_ror:1 row_mask:0xf bank_mask:0xf
	v_mov_b32_dpp v75, v69 row_ror:1 row_mask:0xf bank_mask:0xf
	v_cndmask_b32_e32 v73, v73, v94, vcc
	v_cndmask_b32_e32 v72, v72, v90, vcc
	v_pk_mul_f32 v[72:73], v[126:127], v[72:73]
	v_cndmask_b32_e64 v75, v75, v93, s[38:39]
	v_cndmask_b32_e64 v74, v74, v80, s[38:39]
	v_pk_fma_f32 v[72:73], v[118:119], v[74:75], v[72:73]
	v_mov_b32_dpp v77, v64 row_ror:2 row_mask:0xf bank_mask:0xf
	v_pk_fma_f32 v[68:69], v[68:69], v[114:115], v[72:73]
	v_mov_b32_dpp v79, v65 row_ror:2 row_mask:0xf bank_mask:0xf
	v_pk_add_f32 v[68:69], v[122:123], v[68:69]
	v_mov_b32_dpp v76, v64 row_ror:1 row_mask:0xf bank_mask:0xf
	v_mul_f32_e32 v72, 0xbfb8aa3b, v68
	v_mul_f32_e32 v73, 0xbfb8aa3b, v69
	v_exp_f32_e32 v72, v72
	v_exp_f32_e32 v73, v73
	v_mov_b32_dpp v78, v65 row_ror:1 row_mask:0xf bank_mask:0xf
	v_cndmask_b32_e32 v75, v79, v132, vcc
	v_cndmask_b32_e32 v74, v77, v92, vcc
	v_pk_mul_f32 v[74:75], v[110:111], v[74:75]
	v_cndmask_b32_e64 v77, v78, v95, s[38:39]
	v_cndmask_b32_e64 v76, v76, v91, s[38:39]
	v_mov_b32_dpp v85, v70 row_ror:2 row_mask:0xf bank_mask:0xf
	v_mov_b32_dpp v80, v71 row_ror:2 row_mask:0xf bank_mask:0xf
	v_add_f32_e32 v72, 1.0, v72
	v_pk_fma_f32 v[74:75], v[98:99], v[76:77], v[74:75]
	v_add_f32_e32 v73, 1.0, v73
	v_mov_b32_dpp v84, v70 row_ror:1 row_mask:0xf bank_mask:0xf
	v_mov_b32_dpp v88, v71 row_ror:1 row_mask:0xf bank_mask:0xf
	v_rcp_f32_e32 v72, v72
	v_pk_fma_f32 v[64:65], v[64:65], v[102:103], v[74:75]
	v_rcp_f32_e32 v73, v73
	v_cndmask_b32_e32 v75, v80, v138, vcc
	v_cndmask_b32_e32 v74, v85, v134, vcc
	v_pk_mul_f32 v[74:75], v[128:129], v[74:75]
	v_cndmask_b32_e64 v77, v88, v137, s[38:39]
	v_cndmask_b32_e64 v76, v84, v133, s[38:39]
	v_pk_fma_f32 v[74:75], v[120:121], v[76:77], v[74:75]
	v_pk_add_f32 v[64:65], v[106:107], v[64:65]
	v_pk_fma_f32 v[70:71], v[70:71], v[116:117], v[74:75]
	v_pk_mul_f32 v[68:69], v[68:69], v[72:73]
	v_pk_add_f32 v[70:71], v[124:125], v[70:71]
	v_pk_mul_f32 v[64:65], v[64:65], v[68:69]
	v_mul_f32_e32 v74, 0xbfb8aa3b, v70
	v_mul_f32_e32 v69, 0xbfb8aa3b, v71
	v_exp_f32_e32 v74, v74
	v_exp_f32_e32 v69, v69
	v_mov_b32_dpp v87, v66 row_ror:2 row_mask:0xf bank_mask:0xf
	v_mov_b32_dpp v90, v67 row_ror:2 row_mask:0xf bank_mask:0xf
	v_add_f32_e32 v68, 1.0, v74
	v_add_f32_e32 v69, 1.0, v69
	v_mov_b32_dpp v86, v66 row_ror:1 row_mask:0xf bank_mask:0xf
	v_mov_b32_dpp v89, v67 row_ror:1 row_mask:0xf bank_mask:0xf
	v_rcp_f32_e32 v68, v68
	v_cndmask_b32_e32 v73, v90, v140, vcc
	v_cndmask_b32_e32 v72, v87, v136, vcc
	v_rcp_f32_e32 v69, v69
	v_pk_mul_f32 v[72:73], v[112:113], v[72:73]
	v_cndmask_b32_e64 v75, v89, v139, s[38:39]
	v_cndmask_b32_e64 v74, v86, v135, s[38:39]
	v_pk_fma_f32 v[72:73], v[100:101], v[74:75], v[72:73]
	v_pk_mul_f32 v[68:69], v[70:71], v[68:69]
	v_pk_fma_f32 v[66:67], v[66:67], v[104:105], v[72:73]
	s_nop 0
	v_pk_add_f32 v[66:67], v[108:109], v[66:67]
	s_nop 0
	v_pk_mul_f32 v[66:67], v[66:67], v[68:69]
	s_nop 0
	v_cvt_pk_bf16_f32 v67, v66, v67
	v_cvt_pk_bf16_f32 v66, v64, v65
	v_lshl_add_u64 v[64:65], s[20:21], 0, v[82:83]
	global_store_dwordx2 v[64:65], v[66:67], off
	s_add_i32 s70, s63, 0x80
	s_ashr_i32 s12, s70, 6
	s_mul_hi_i32 s3, s12, 0xb000
	s_mul_i32 s12, s12, 0xb000
	s_and_saveexec_b64 s[4:5], vcc
	s_cbranch_execz .LBB0_572
	s_add_u32 s20, s94, s12
	v_readlane_b32 s13, v255, 43
	s_addc_u32 s21, s13, s3
	s_movk_i32 s13, 0x1600
	v_mad_u64_u32 v[68:69], s[80:81], v189, s13, v[186:187]
	v_mov_b32_e32 v69, v81
	v_cvt_pk_bf16_f32 v64, v60, v61
	v_cvt_pk_bf16_f32 v65, v62, v63
	v_cvt_pk_bf16_f32 v66, v28, v29
	v_cvt_pk_bf16_f32 v67, v30, v31
	v_lshl_add_u64 v[70:71], v[68:69], 1, s[20:21]
	v_add_u32_e32 v80, 0x80, v68
	global_store_dwordx4 v[70:71], v[64:67], off
	v_lshl_add_u64 v[68:69], v[80:81], 1, s[20:21]
	s_nop 0
	v_cvt_pk_bf16_f32 v64, v56, v57
	v_cvt_pk_bf16_f32 v65, v58, v59
	v_cvt_pk_bf16_f32 v66, v24, v25
	v_cvt_pk_bf16_f32 v67, v26, v27
	global_store_dwordx4 v[68:69], v[64:67], off
;     __device__ __forceinline__ void operator()(const f32x4 (&acc)[2][2][4][2], const Unit& u, int wr, int wc, int fr_, int fq_) const {
;     ...
;             for (int mm = 0; mm < 2; ++mm) { const int m = mm * 3;
;                 const bool is_edge = mm == 0 ? (fr < 2) : (fr >= 14);
;                 if (is_edge) { const unsigned e = (unsigned)(mm == 0 ? fr : fr - 12);
;                     bf16_t* eb = edge + (size_t)grp * 4 * 5632;
; #pragma unroll
;                     for (int bj = 0; bj < 2; ++bj) { const f32x4 v0 = acc[ai][bj][m][0], v1 = acc[ai][bj][m][1];
;                         u32x4 w; w.x = cvt_pk_bf16(v0[0], v0[1]); w.y = cvt_pk_bf16(v0[2], v0[3]); w.z = cvt_pk_bf16(v1[0], v1[1]); w.w = cvt_pk_bf16(v1[2], v1[3]);
;                         *(u32x4*)(eb + (e * 5632u + ecol + (unsigned)(bj * HALF))) = w; } } }
; #pragma unroll
;             for (int n = 0; n < 2; ++n) {
;                 int jl = jbase + 4 * n; asm volatile("" : "+v"(jl) :: "memory");
;                 const unsigned j = (unsigned)jl;
;                 const f32x4 wg0 = *(const f32x4*)(cw + j), wg1 = *(const f32x4*)(cw + 5632 + j), wg2 = *(const f32x4*)(cw + 2 * 5632 + j), bg = *(const f32x4*)(cb + j);
;                 const f32x4 wv0 = *(const f32x4*)(cw + 2816 + j), wv1 = *(const f32x4*)(cw + 5632 + 2816 + j), wv2 = *(const f32x4*)(cw + 2 * 5632 + 2816 + j), bv = *(const f32x4*)(cb + 2816 + j);
;                 const unsigned loff = (unsigned)fr * 2816u + j;
;                 const bool c1 = fr == 0, c2 = fr < 2;
;                 f32x4 g1p = (f32x4){0.f, 0.f, 0.f, 0.f}, g2p = g1p, v1p = g1p, v2p = g1p;
; #pragma unroll
;                 for (int m = 0; m < 4; ++m) {
;                     const f32x4 xg = acc[ai][0][m][n], xv = acc[ai][1][m][n];
;                     f32x4 g1, g2, v1, v2;
; #pragma unroll
;                     for (int i = 0; i < 4; ++i) { g1[i] = dpp_ror1(xg[i]); g2[i] = dpp_ror2(xg[i]); v1[i] = dpp_ror1(xv[i]); v2[i] = dpp_ror2(xv[i]); }
;                     f32x4 pg1, pg2, pv1, pv2;
; #pragma unroll
;                     for (int i = 0; i < 4; ++i) { pg1[i] = c1 ? g1p[i] : g1[i]; pg2[i] = c2 ? g2p[i] : g2[i]; pv1[i] = c1 ? v1p[i] : v1[i]; pv2[i] = c2 ? v2p[i] : v2[i]; }
;                     const f32x4 G = wg0 * pg2 + wg1 * pg1 + wg2 * xg + bg;
;                     const f32x4 V = wv0 * pv2 + wv1 * pv1 + wv2 * xv + bv;
;                     f32x4 r;
.LBB0_572:
	s_or_b64 exec, exec, s[4:5]
	s_and_saveexec_b64 s[4:5], s[42:43]
	s_cbranch_execz .LBB0_574
	s_add_u32 s12, s94, s12
	v_readlane_b32 s13, v255, 43
	s_addc_u32 s13, s13, s3
	s_movk_i32 s3, 0x1600
	v_mad_u64_u32 v[68:69], s[20:21], v223, s3, v[186:187]
	v_mov_b32_e32 v69, v81
	v_cvt_pk_bf16_f32 v64, v36, v37
	v_cvt_pk_bf16_f32 v65, v38, v39
	v_cvt_pk_bf16_f32 v66, v4, v5
	v_cvt_pk_bf16_f32 v67, v6, v7
	v_lshl_add_u64 v[70:71], v[68:69], 1, s[12:13]
	v_add_u32_e32 v80, 0x80, v68
	global_store_dwordx4 v[70:71], v[64:67], off
	v_lshl_add_u64 v[68:69], v[80:81], 1, s[12:13]
	s_nop 0
	v_cvt_pk_bf16_f32 v64, v32, v33
	v_cvt_pk_bf16_f32 v65, v34, v35
	v_cvt_pk_bf16_f32 v66, v0, v1
	v_cvt_pk_bf16_f32 v67, v2, v3
	global_store_dwordx4 v[68:69], v[64:67], off
.LBB0_574:
	s_or_b64 exec, exec, s[4:5]
	v_mov_b32_e32 v189, v81
	v_mov_b32_dpp v110, v60 row_ror:1 row_mask:0xf bank_mask:0xf
	v_lshlrev_b32_e32 v72, 2, v188
	v_and_b32_e32 v72, 0x1ff, v72
	v_add_u32_e32 v72, s101, v72
	ds_read_b128 v[94:97], v72 offset:0
	ds_read_b128 v[82:85], v72 offset:512
	ds_read_b128 v[86:89], v72 offset:1024
	ds_read_b128 v[90:93], v72 offset:1536
	ds_read_b128 v[76:79], v72 offset:2048
	s_nop 0
	ds_read_b128 v[64:67], v72 offset:2560
	v_add_u32_e32 v80, v188, v222
	ds_read_b128 v[68:71], v72 offset:3072
	v_mov_b32_dpp v112, v60 row_ror:2 row_mask:0xf bank_mask:0xf
	ds_read_b128 v[72:75], v72 offset:3584
	v_mov_b32_dpp v104, v56 row_ror:1 row_mask:0xf bank_mask:0xf
	v_mov_b32_dpp v108, v56 row_ror:2 row_mask:0xf bank_mask:0xf
	v_mov_b32_dpp v111, v61 row_ror:1 row_mask:0xf bank_mask:0xf
	v_mov_b32_dpp v113, v61 row_ror:2 row_mask:0xf bank_mask:0xf
	v_mov_b32_dpp v105, v57 row_ror:1 row_mask:0xf bank_mask:0xf
	v_mov_b32_dpp v109, v57 row_ror:2 row_mask:0xf bank_mask:0xf
	v_mov_b32_dpp v102, v62 row_ror:1 row_mask:0xf bank_mask:0xf
	v_mov_b32_dpp v106, v62 row_ror:2 row_mask:0xf bank_mask:0xf
	v_mov_b32_dpp v98, v58 row_ror:1 row_mask:0xf bank_mask:0xf
	v_mov_b32_dpp v100, v58 row_ror:2 row_mask:0xf bank_mask:0xf
	v_mov_b32_dpp v103, v63 row_ror:1 row_mask:0xf bank_mask:0xf
	v_mov_b32_dpp v107, v63 row_ror:2 row_mask:0xf bank_mask:0xf
	v_mov_b32_dpp v99, v59 row_ror:1 row_mask:0xf bank_mask:0xf
	v_mov_b32_dpp v101, v59 row_ror:2 row_mask:0xf bank_mask:0xf
	s_and_saveexec_b64 s[4:5], s[40:41]
	s_xor_b64 s[4:5], exec, s[4:5]
	s_cbranch_execz .LBB0_576
	s_waitcnt lgkmcnt(0)
	v_pk_mul_f32 v[114:115], v[94:95], v[112:113]
	v_pk_mul_f32 v[116:117], v[76:77], v[108:109]
	v_pk_fma_f32 v[114:115], v[82:83], v[110:111], v[114:115]
	v_pk_fma_f32 v[116:117], v[64:65], v[104:105], v[116:117]
	v_pk_fma_f32 v[60:61], v[60:61], v[86:87], v[114:115]
	v_pk_fma_f32 v[56:57], v[56:57], v[68:69], v[116:117]
	v_pk_add_f32 v[60:61], v[90:91], v[60:61]
	v_pk_add_f32 v[56:57], v[72:73], v[56:57]
	v_mul_f32_e32 v114, 0xbfb8aa3b, v60
	v_mul_f32_e32 v115, 0xbfb8aa3b, v61
	v_exp_f32_e32 v114, v114
	v_exp_f32_e32 v115, v115
	s_mul_i32 s12, s70, 0x1600
	s_mul_hi_i32 s3, s70, 0x1600
	v_add_f32_e32 v114, 1.0, v114
	v_add_f32_e32 v115, 1.0, v115
	v_rcp_f32_e32 v114, v114
	v_rcp_f32_e32 v115, v115
	s_add_u32 s12, s79, s12
	s_addc_u32 s13, s84, s3
	v_pk_mul_f32 v[60:61], v[60:61], v[114:115]
	s_nop 0
	v_pk_mul_f32 v[56:57], v[56:57], v[60:61]
	v_pk_mul_f32 v[60:61], v[96:97], v[106:107]
	v_pk_mul_f32 v[114:115], v[78:79], v[100:101]
	v_pk_fma_f32 v[60:61], v[84:85], v[102:103], v[60:61]
	v_pk_fma_f32 v[114:115], v[66:67], v[98:99], v[114:115]
	v_pk_fma_f32 v[60:61], v[62:63], v[88:89], v[60:61]
	v_pk_fma_f32 v[58:59], v[58:59], v[70:71], v[114:115]
	v_pk_add_f32 v[60:61], v[92:93], v[60:61]
	v_pk_add_f32 v[58:59], v[74:75], v[58:59]
	v_mul_f32_e32 v62, 0xbfb8aa3b, v60
	v_mul_f32_e32 v63, 0xbfb8aa3b, v61
	v_exp_f32_e32 v62, v62
	v_exp_f32_e32 v63, v63
	v_add_f32_e32 v62, 1.0, v62
	v_add_f32_e32 v63, 1.0, v63
	v_rcp_f32_e32 v62, v62
	v_rcp_f32_e32 v63, v63
	s_nop 0
	v_pk_mul_f32 v[60:61], v[60:61], v[62:63]
	s_nop 0
	v_pk_mul_f32 v[58:59], v[58:59], v[60:61]
	s_nop 0
	v_cvt_pk_bf16_f32 v59, v58, v59
	v_cvt_pk_bf16_f32 v58, v56, v57
	v_lshl_add_u64 v[56:57], v[80:81], 1, s[12:13]
	global_store_dwordx2 v[56:57], v[58:59], off
.LBB0_576:
	s_andn2_saveexec_b64 s[4:5], s[4:5]
	s_or_b64 exec, exec, s[4:5]
	v_mov_b32_dpp v63, v52 row_ror:2 row_mask:0xf bank_mask:0xf
	v_mov_b32_dpp v117, v53 row_ror:2 row_mask:0xf bank_mask:0xf
	v_mov_b32_dpp v62, v52 row_ror:1 row_mask:0xf bank_mask:0xf
	v_mov_b32_dpp v116, v53 row_ror:1 row_mask:0xf bank_mask:0xf
	v_cndmask_b32_e32 v57, v117, v113, vcc
	v_cndmask_b32_e32 v56, v63, v112, vcc
	s_waitcnt lgkmcnt(0)
; __device__ __forceinline__ unsigned cvt_pk_bf16(float lo, float hi) { f32x2_cv v = {lo, hi}; bf16x2_cv b = __builtin_convertvector(v, bf16x2_cv); return __builtin_bit_cast(unsigned, b); }
; __device__ __forceinline__ float dpp_ror1(float v) { return __builtin_bit_cast(float, __builtin_amdgcn_mov_dpp(__builtin_bit_cast(int, v), 0x121, 0xf, 0xf, false)); }
; __device__ __forceinline__ float dpp_ror2(float v) { return __builtin_bit_cast(float, __builtin_amdgcn_mov_dpp(__builtin_bit_cast(int, v), 0x122, 0xf, 0xf, false)); }
;     __device__ __forceinline__ void operator()(const f32x4 (&acc)[2][2][4][2], const Unit& u, int wr, int wc, int fr_, int fq_) const {
;     ...
;                 for (int m = 0; m < 4; ++m) {
;                     const f32x4 xg = acc[ai][0][m][n], xv = acc[ai][1][m][n];
;                     f32x4 g1, g2, v1, v2;
; #pragma unroll
;                     for (int i = 0; i < 4; ++i) { g1[i] = dpp_ror1(xg[i]); g2[i] = dpp_ror2(xg[i]); v1[i] = dpp_ror1(xv[i]); v2[i] = dpp_ror2(xv[i]); }
;                     f32x4 pg1, pg2, pv1, pv2;
; #pragma unroll
;                     for (int i = 0; i < 4; ++i) { pg1[i] = c1 ? g1p[i] : g1[i]; pg2[i] = c2 ? g2p[i] : g2[i]; pv1[i] = c1 ? v1p[i] : v1[i]; pv2[i] = c2 ? v2p[i] : v2[i]; }
;                     const f32x4 G = wg0 * pg2 + wg1 * pg1 + wg2 * xg + bg;
;                     const f32x4 V = wv0 * pv2 + wv1 * pv1 + wv2 * xv + bv;
;                     f32x4 r;
; #pragma unroll
;                     for (int i = 0; i < 4; ++i) r[i] = G[i] * __builtin_amdgcn_rcpf(1.0f + __builtin_amdgcn_exp2f(-1.4426950408889634f * G[i])) * V[i];
;                     u32x2 w; w.x = cvt_pk_bf16(r[0], r[1]); w.y = cvt_pk_bf16(r[2], r[3]);
;                     if (m > 0 || !c2) *(u32x2*)(ACT + (size_t)(rowu + ai * HALF + m * 16) * 2816 + loff) = w;
;                     g1p = g1; g2p = g2; v1p = v1; v2p = v2;
	v_pk_mul_f32 v[56:57], v[94:95], v[56:57]
	v_cndmask_b32_e64 v59, v116, v111, s[38:39]
	v_cndmask_b32_e64 v58, v62, v110, s[38:39]
	v_pk_fma_f32 v[56:57], v[82:83], v[58:59], v[56:57]
	v_mov_b32_dpp v115, v48 row_ror:2 row_mask:0xf bank_mask:0xf
	v_pk_fma_f32 v[52:53], v[52:53], v[86:87], v[56:57]
	v_mov_b32_dpp v119, v49 row_ror:2 row_mask:0xf bank_mask:0xf
	v_pk_add_f32 v[52:53], v[90:91], v[52:53]
	v_mov_b32_dpp v114, v48 row_ror:1 row_mask:0xf bank_mask:0xf
	v_mul_f32_e32 v56, 0xbfb8aa3b, v52
	v_mul_f32_e32 v57, 0xbfb8aa3b, v53
	v_exp_f32_e32 v56, v56
	v_exp_f32_e32 v57, v57
	v_mov_b32_dpp v118, v49 row_ror:1 row_mask:0xf bank_mask:0xf
	v_cndmask_b32_e32 v59, v119, v109, vcc
	v_cndmask_b32_e32 v58, v115, v108, vcc
	v_pk_mul_f32 v[58:59], v[76:77], v[58:59]
	v_cndmask_b32_e64 v61, v118, v105, s[38:39]
	v_cndmask_b32_e64 v60, v114, v104, s[38:39]
	v_mov_b32_dpp v121, v54 row_ror:2 row_mask:0xf bank_mask:0xf
	v_mov_b32_dpp v110, v55 row_ror:2 row_mask:0xf bank_mask:0xf
	v_add_f32_e32 v56, 1.0, v56
	v_pk_fma_f32 v[58:59], v[64:65], v[60:61], v[58:59]
	v_add_f32_e32 v57, 1.0, v57
	v_mov_b32_dpp v120, v54 row_ror:1 row_mask:0xf bank_mask:0xf
	v_mov_b32_dpp v124, v55 row_ror:1 row_mask:0xf bank_mask:0xf
	v_rcp_f32_e32 v56, v56
	v_pk_fma_f32 v[48:49], v[48:49], v[68:69], v[58:59]
	v_rcp_f32_e32 v57, v57
	v_cndmask_b32_e32 v59, v110, v107, vcc
	v_cndmask_b32_e32 v58, v121, v106, vcc
	v_pk_mul_f32 v[58:59], v[96:97], v[58:59]
	v_cndmask_b32_e64 v61, v124, v103, s[38:39]
	v_cndmask_b32_e64 v60, v120, v102, s[38:39]
	v_pk_fma_f32 v[58:59], v[84:85], v[60:61], v[58:59]
	v_pk_add_f32 v[48:49], v[72:73], v[48:49]
	v_pk_fma_f32 v[54:55], v[54:55], v[88:89], v[58:59]
	v_pk_mul_f32 v[52:53], v[52:53], v[56:57]
	v_pk_add_f32 v[54:55], v[92:93], v[54:55]
	v_pk_mul_f32 v[48:49], v[48:49], v[52:53]
	v_mul_f32_e32 v58, 0xbfb8aa3b, v54
	v_mul_f32_e32 v53, 0xbfb8aa3b, v55
	v_exp_f32_e32 v58, v58
	v_exp_f32_e32 v53, v53
	v_mov_b32_dpp v123, v50 row_ror:2 row_mask:0xf bank_mask:0xf
	v_mov_b32_dpp v112, v51 row_ror:2 row_mask:0xf bank_mask:0xf
	v_add_f32_e32 v52, 1.0, v58
	v_add_f32_e32 v53, 1.0, v53
	v_mov_b32_dpp v122, v50 row_ror:1 row_mask:0xf bank_mask:0xf
	v_mov_b32_dpp v111, v51 row_ror:1 row_mask:0xf bank_mask:0xf
	v_rcp_f32_e32 v52, v52
	v_cndmask_b32_e32 v57, v112, v101, vcc
	v_cndmask_b32_e32 v56, v123, v100, vcc
	v_rcp_f32_e32 v53, v53
	v_pk_mul_f32 v[56:57], v[78:79], v[56:57]
	v_cndmask_b32_e64 v59, v111, v99, s[38:39]
	v_cndmask_b32_e64 v58, v122, v98, s[38:39]
	v_pk_fma_f32 v[56:57], v[66:67], v[58:59], v[56:57]
	v_pk_mul_f32 v[52:53], v[54:55], v[52:53]
	v_pk_fma_f32 v[50:51], v[50:51], v[70:71], v[56:57]
	s_add_i32 s3, s63, 0x90
	v_pk_add_f32 v[50:51], v[74:75], v[50:51]
	s_add_i32 s4, s65, 0xc6000
	v_pk_mul_f32 v[50:51], v[50:51], v[52:53]
	s_mul_hi_i32 s3, s3, 0x1600
	s_add_u32 s4, s79, s4
	v_cvt_pk_bf16_f32 v51, v50, v51
	v_cvt_pk_bf16_f32 v50, v48, v49
	s_addc_u32 s5, s84, s3
	v_lshlrev_b64 v[48:49], 1, v[80:81]
	v_lshl_add_u64 v[52:53], s[4:5], 0, v[48:49]
	global_store_dwordx2 v[52:53], v[50:51], off
	v_mov_b32_dpp v57, v44 row_ror:2 row_mask:0xf bank_mask:0xf
	v_mov_b32_dpp v61, v45 row_ror:2 row_mask:0xf bank_mask:0xf
	v_mov_b32_dpp v56, v44 row_ror:1 row_mask:0xf bank_mask:0xf
	v_mov_b32_dpp v60, v45 row_ror:1 row_mask:0xf bank_mask:0xf
	v_cndmask_b32_e32 v51, v61, v117, vcc
	v_cndmask_b32_e32 v50, v57, v63, vcc
	v_pk_mul_f32 v[50:51], v[94:95], v[50:51]
	v_cndmask_b32_e64 v53, v60, v116, s[38:39]
	v_cndmask_b32_e64 v52, v56, v62, s[38:39]
	v_pk_fma_f32 v[50:51], v[82:83], v[52:53], v[50:51]
	v_mov_b32_dpp v59, v40 row_ror:2 row_mask:0xf bank_mask:0xf
	v_pk_fma_f32 v[44:45], v[44:45], v[86:87], v[50:51]
	v_mov_b32_dpp v98, v41 row_ror:2 row_mask:0xf bank_mask:0xf
	v_pk_add_f32 v[44:45], v[90:91], v[44:45]
	v_mov_b32_dpp v58, v40 row_ror:1 row_mask:0xf bank_mask:0xf
	v_mul_f32_e32 v50, 0xbfb8aa3b, v44
	v_mul_f32_e32 v51, 0xbfb8aa3b, v45
	v_exp_f32_e32 v50, v50
	v_exp_f32_e32 v51, v51
	v_mov_b32_dpp v80, v41 row_ror:1 row_mask:0xf bank_mask:0xf
	v_cndmask_b32_e32 v53, v98, v119, vcc
	v_add_f32_e32 v50, 1.0, v50
	v_add_f32_e32 v51, 1.0, v51
	v_rcp_f32_e32 v50, v50
	v_cndmask_b32_e32 v52, v59, v115, vcc
	v_rcp_f32_e32 v51, v51
	v_pk_mul_f32 v[52:53], v[76:77], v[52:53]
	v_cndmask_b32_e64 v55, v80, v118, s[38:39]
	v_cndmask_b32_e64 v54, v58, v114, s[38:39]
	v_pk_fma_f32 v[52:53], v[64:65], v[54:55], v[52:53]
	v_mov_b32_dpp v100, v46 row_ror:2 row_mask:0xf bank_mask:0xf
	v_pk_fma_f32 v[40:41], v[40:41], v[68:69], v[52:53]
	v_mov_b32_dpp v104, v47 row_ror:2 row_mask:0xf bank_mask:0xf
	v_pk_add_f32 v[40:41], v[72:73], v[40:41]
	v_pk_mul_f32 v[44:45], v[44:45], v[50:51]
	v_mov_b32_dpp v99, v46 row_ror:1 row_mask:0xf bank_mask:0xf
	v_mov_b32_dpp v103, v47 row_ror:1 row_mask:0xf bank_mask:0xf
	v_pk_mul_f32 v[40:41], v[40:41], v[44:45]
	v_cndmask_b32_e32 v45, v104, v110, vcc
	v_cndmask_b32_e32 v44, v100, v121, vcc
	v_pk_mul_f32 v[44:45], v[96:97], v[44:45]
	v_cndmask_b32_e64 v51, v103, v124, s[38:39]
	v_cndmask_b32_e64 v50, v99, v120, s[38:39]
	v_pk_fma_f32 v[44:45], v[84:85], v[50:51], v[44:45]
	v_mov_b32_dpp v102, v42 row_ror:2 row_mask:0xf bank_mask:0xf
	v_pk_fma_f32 v[44:45], v[46:47], v[88:89], v[44:45]
	v_mov_b32_dpp v106, v43 row_ror:2 row_mask:0xf bank_mask:0xf
	v_pk_add_f32 v[44:45], v[92:93], v[44:45]
	v_mov_b32_dpp v101, v42 row_ror:1 row_mask:0xf bank_mask:0xf
	v_mul_f32_e32 v46, 0xbfb8aa3b, v44
	v_mul_f32_e32 v47, 0xbfb8aa3b, v45
	v_exp_f32_e32 v46, v46
	v_exp_f32_e32 v47, v47
	v_mov_b32_dpp v105, v43 row_ror:1 row_mask:0xf bank_mask:0xf
	v_cndmask_b32_e32 v51, v106, v112, vcc
	v_add_f32_e32 v46, 1.0, v46
	v_add_f32_e32 v47, 1.0, v47
; __device__ __forceinline__ unsigned cvt_pk_bf16(float lo, float hi) { f32x2_cv v = {lo, hi}; bf16x2_cv b = __builtin_convertvector(v, bf16x2_cv); return __builtin_bit_cast(unsigned, b); }
;     __device__ __forceinline__ void operator()(const f32x4 (&acc)[2][2][4][2], const Unit& u, int wr, int wc, int fr_, int fq_) const {
;     ...
;             for (int n = 0; n < 2; ++n) {
;                 int jl = jbase + 4 * n; asm volatile("" : "+v"(jl) :: "memory");
;                 const unsigned j = (unsigned)jl;
;                 const f32x4 wg0 = *(const f32x4*)(cw + j), wg1 = *(const f32x4*)(cw + 5632 + j), wg2 = *(const f32x4*)(cw + 2 * 5632 + j), bg = *(const f32x4*)(cb + j);
;                 const f32x4 wv0 = *(const f32x4*)(cw + 2816 + j), wv1 = *(const f32x4*)(cw + 5632 + 2816 + j), wv2 = *(const f32x4*)(cw + 2 * 5632 + 2816 + j), bv = *(const f32x4*)(cb + 2816 + j);
;                 const unsigned loff = (unsigned)fr * 2816u + j;
;                 const bool c1 = fr == 0, c2 = fr < 2;
;                 f32x4 g1p = (f32x4){0.f, 0.f, 0.f, 0.f}, g2p = g1p, v1p = g1p, v2p = g1p;
; #pragma unroll
;                 for (int m = 0; m < 4; ++m) {
;                     const f32x4 xg = acc[ai][0][m][n], xv = acc[ai][1][m][n];
;                     f32x4 g1, g2, v1, v2;
; #pragma unroll
;                     for (int i = 0; i < 4; ++i) { g1[i] = dpp_ror1(xg[i]); g2[i] = dpp_ror2(xg[i]); v1[i] = dpp_ror1(xv[i]); v2[i] = dpp_ror2(xv[i]); }
;                     f32x4 pg1, pg2, pv1, pv2;
; #pragma unroll
;                     for (int i = 0; i < 4; ++i) { pg1[i] = c1 ? g1p[i] : g1[i]; pg2[i] = c2 ? g2p[i] : g2[i]; pv1[i] = c1 ? v1p[i] : v1[i]; pv2[i] = c2 ? v2p[i] : v2[i]; }
;                     const f32x4 G = wg0 * pg2 + wg1 * pg1 + wg2 * xg + bg;
;                     const f32x4 V = wv0 * pv2 + wv1 * pv1 + wv2 * xv + bv;
;                     f32x4 r;
; #pragma unroll
;                     for (int i = 0; i < 4; ++i) r[i] = G[i] * __builtin_amdgcn_rcpf(1.0f + __builtin_amdgcn_exp2f(-1.4426950408889634f * G[i])) * V[i];
;                     u32x2 w; w.x = cvt_pk_bf16(r[0], r[1]); w.y = cvt_pk_bf16(r[2], r[3]);
;                     if (m > 0 || !c2) *(u32x2*)(ACT + (size_t)(rowu + ai * HALF + m * 16) * 2816 + loff) = w;
;                     g1p = g1; g2p = g2; v1p = v1; v2p = v2;
	v_rcp_f32_e32 v46, v46
	v_cndmask_b32_e32 v50, v102, v123, vcc
	v_rcp_f32_e32 v47, v47
	v_pk_mul_f32 v[50:51], v[78:79], v[50:51]
	v_cndmask_b32_e64 v53, v105, v111, s[38:39]
	v_cndmask_b32_e64 v52, v101, v122, s[38:39]
	v_pk_fma_f32 v[50:51], v[66:67], v[52:53], v[50:51]
	s_add_i32 s3, s63, 0xa0
	v_pk_fma_f32 v[42:43], v[42:43], v[70:71], v[50:51]
	s_add_i32 s12, s65, 0xdc000
	v_pk_add_f32 v[42:43], v[74:75], v[42:43]
	v_pk_mul_f32 v[44:45], v[44:45], v[46:47]
	s_mul_hi_i32 s3, s3, 0x1600
	s_add_u32 s12, s79, s12
	v_pk_mul_f32 v[42:43], v[42:43], v[44:45]
	s_addc_u32 s13, s84, s3
	v_cvt_pk_bf16_f32 v43, v42, v43
	v_cvt_pk_bf16_f32 v42, v40, v41
	v_lshl_add_u64 v[40:41], s[12:13], 0, v[48:49]
	global_store_dwordx2 v[40:41], v[42:43], off
	s_nop 0
	v_mov_b32_dpp v40, v36 row_ror:2 row_mask:0xf bank_mask:0xf
	v_mov_b32_dpp v41, v37 row_ror:2 row_mask:0xf bank_mask:0xf
	v_mov_b32_dpp v42, v36 row_ror:1 row_mask:0xf bank_mask:0xf
	v_mov_b32_dpp v43, v37 row_ror:1 row_mask:0xf bank_mask:0xf
	v_cndmask_b32_e32 v41, v41, v61, vcc
	v_cndmask_b32_e32 v40, v40, v57, vcc
	v_pk_mul_f32 v[40:41], v[94:95], v[40:41]
	v_cndmask_b32_e64 v43, v43, v60, s[38:39]
	v_cndmask_b32_e64 v42, v42, v56, s[38:39]
	v_pk_fma_f32 v[40:41], v[82:83], v[42:43], v[40:41]
	v_mov_b32_dpp v45, v32 row_ror:2 row_mask:0xf bank_mask:0xf
	v_pk_fma_f32 v[36:37], v[36:37], v[86:87], v[40:41]
	v_mov_b32_dpp v47, v33 row_ror:2 row_mask:0xf bank_mask:0xf
	v_pk_add_f32 v[36:37], v[90:91], v[36:37]
	v_mov_b32_dpp v44, v32 row_ror:1 row_mask:0xf bank_mask:0xf
	v_mul_f32_e32 v40, 0xbfb8aa3b, v36
	v_mul_f32_e32 v41, 0xbfb8aa3b, v37
	v_exp_f32_e32 v40, v40
	v_exp_f32_e32 v41, v41
	v_mov_b32_dpp v46, v33 row_ror:1 row_mask:0xf bank_mask:0xf
	v_cndmask_b32_e32 v43, v47, v98, vcc
	v_cndmask_b32_e32 v42, v45, v59, vcc
	v_pk_mul_f32 v[42:43], v[76:77], v[42:43]
	v_cndmask_b32_e64 v45, v46, v80, s[38:39]
	v_cndmask_b32_e64 v44, v44, v58, s[38:39]
	v_mov_b32_dpp v51, v38 row_ror:2 row_mask:0xf bank_mask:0xf
	v_mov_b32_dpp v55, v39 row_ror:2 row_mask:0xf bank_mask:0xf
	v_add_f32_e32 v40, 1.0, v40
	v_pk_fma_f32 v[42:43], v[64:65], v[44:45], v[42:43]
	v_add_f32_e32 v41, 1.0, v41
	v_mov_b32_dpp v50, v38 row_ror:1 row_mask:0xf bank_mask:0xf
	v_mov_b32_dpp v54, v39 row_ror:1 row_mask:0xf bank_mask:0xf
	v_rcp_f32_e32 v40, v40
	v_pk_fma_f32 v[32:33], v[32:33], v[68:69], v[42:43]
	v_rcp_f32_e32 v41, v41
	v_cndmask_b32_e32 v43, v55, v104, vcc
	v_cndmask_b32_e32 v42, v51, v100, vcc
	v_pk_mul_f32 v[42:43], v[96:97], v[42:43]
	v_cndmask_b32_e64 v45, v54, v103, s[38:39]
	v_cndmask_b32_e64 v44, v50, v99, s[38:39]
	v_pk_fma_f32 v[42:43], v[84:85], v[44:45], v[42:43]
	v_pk_add_f32 v[32:33], v[72:73], v[32:33]
	v_pk_fma_f32 v[38:39], v[38:39], v[88:89], v[42:43]
	v_pk_mul_f32 v[36:37], v[36:37], v[40:41]
	v_pk_add_f32 v[38:39], v[92:93], v[38:39]
	v_pk_mul_f32 v[32:33], v[32:33], v[36:37]
	v_mul_f32_e32 v42, 0xbfb8aa3b, v38
	v_mul_f32_e32 v37, 0xbfb8aa3b, v39
	v_exp_f32_e32 v42, v42
	v_exp_f32_e32 v37, v37
	v_mov_b32_dpp v53, v34 row_ror:2 row_mask:0xf bank_mask:0xf
	v_mov_b32_dpp v57, v35 row_ror:2 row_mask:0xf bank_mask:0xf
	v_add_f32_e32 v36, 1.0, v42
	v_add_f32_e32 v37, 1.0, v37
	v_mov_b32_dpp v52, v34 row_ror:1 row_mask:0xf bank_mask:0xf
	v_mov_b32_dpp v56, v35 row_ror:1 row_mask:0xf bank_mask:0xf
	v_rcp_f32_e32 v36, v36
	v_cndmask_b32_e32 v41, v57, v106, vcc
	v_cndmask_b32_e32 v40, v53, v102, vcc
	v_rcp_f32_e32 v37, v37
	v_pk_mul_f32 v[40:41], v[78:79], v[40:41]
	v_cndmask_b32_e64 v43, v56, v105, s[38:39]
	v_cndmask_b32_e64 v42, v52, v101, s[38:39]
	v_pk_fma_f32 v[40:41], v[66:67], v[42:43], v[40:41]
	s_addk_i32 s63, 0xb0
	v_pk_fma_f32 v[34:35], v[34:35], v[70:71], v[40:41]
	s_add_i32 s65, s65, 0xf2000
	v_pk_add_f32 v[34:35], v[74:75], v[34:35]
	v_pk_mul_f32 v[36:37], v[38:39], v[36:37]
	s_mul_hi_i32 s3, s63, 0x1600
	s_add_u32 s20, s79, s65
	v_pk_mul_f32 v[34:35], v[34:35], v[36:37]
	s_addc_u32 s21, s84, s3
	v_cvt_pk_bf16_f32 v35, v34, v35
	v_cvt_pk_bf16_f32 v34, v32, v33
	v_lshl_add_u64 v[32:33], s[20:21], 0, v[48:49]
	global_store_dwordx2 v[32:33], v[34:35], off
	v_mov_b32_e32 v131, v81
	v_mov_b32_dpp v76, v28 row_ror:1 row_mask:0xf bank_mask:0xf
	v_lshlrev_b32_e32 v40, 2, v130
	v_and_b32_e32 v40, 0x1ff, v40
	v_add_u32_e32 v40, s101, v40
	ds_read_b128 v[60:63], v40 offset:0
	ds_read_b128 v[48:51], v40 offset:512
	ds_read_b128 v[52:55], v40 offset:1024
	ds_read_b128 v[56:59], v40 offset:1536
	ds_read_b128 v[44:47], v40 offset:2048
	s_nop 0
	ds_read_b128 v[32:35], v40 offset:2560
	v_add_u32_e32 v80, v130, v222
	ds_read_b128 v[36:39], v40 offset:3072
	v_mov_b32_dpp v78, v28 row_ror:2 row_mask:0xf bank_mask:0xf
	ds_read_b128 v[40:43], v40 offset:3584
	v_mov_b32_dpp v70, v24 row_ror:1 row_mask:0xf bank_mask:0xf
	v_mov_b32_dpp v74, v24 row_ror:2 row_mask:0xf bank_mask:0xf
	v_mov_b32_dpp v77, v29 row_ror:1 row_mask:0xf bank_mask:0xf
	v_mov_b32_dpp v79, v29 row_ror:2 row_mask:0xf bank_mask:0xf
	v_mov_b32_dpp v71, v25 row_ror:1 row_mask:0xf bank_mask:0xf
	v_mov_b32_dpp v75, v25 row_ror:2 row_mask:0xf bank_mask:0xf
	v_mov_b32_dpp v68, v30 row_ror:1 row_mask:0xf bank_mask:0xf
	v_mov_b32_dpp v72, v30 row_ror:2 row_mask:0xf bank_mask:0xf
	v_mov_b32_dpp v64, v26 row_ror:1 row_mask:0xf bank_mask:0xf
	v_mov_b32_dpp v66, v26 row_ror:2 row_mask:0xf bank_mask:0xf
	v_mov_b32_dpp v69, v31 row_ror:1 row_mask:0xf bank_mask:0xf
	v_mov_b32_dpp v73, v31 row_ror:2 row_mask:0xf bank_mask:0xf
	v_mov_b32_dpp v65, v27 row_ror:1 row_mask:0xf bank_mask:0xf
	v_mov_b32_dpp v67, v27 row_ror:2 row_mask:0xf bank_mask:0xf
	s_and_saveexec_b64 s[42:43], s[40:41]
	s_xor_b64 s[40:41], exec, s[42:43]
	s_cbranch_execz .LBB0_578
; __device__ __forceinline__ unsigned cvt_pk_bf16(float lo, float hi) { f32x2_cv v = {lo, hi}; bf16x2_cv b = __builtin_convertvector(v, bf16x2_cv); return __builtin_bit_cast(unsigned, b); }
; __device__ __forceinline__ float dpp_ror1(float v) { return __builtin_bit_cast(float, __builtin_amdgcn_mov_dpp(__builtin_bit_cast(int, v), 0x121, 0xf, 0xf, false)); }
; __device__ __forceinline__ float dpp_ror2(float v) { return __builtin_bit_cast(float, __builtin_amdgcn_mov_dpp(__builtin_bit_cast(int, v), 0x122, 0xf, 0xf, false)); }
;     __device__ __forceinline__ void operator()(const f32x4 (&acc)[2][2][4][2], const Unit& u, int wr, int wc, int fr_, int fq_) const {
;     ...
;                 for (int m = 0; m < 4; ++m) {
;                     const f32x4 xg = acc[ai][0][m][n], xv = acc[ai][1][m][n];
;                     f32x4 g1, g2, v1, v2;
; #pragma unroll
;                     for (int i = 0; i < 4; ++i) { g1[i] = dpp_ror1(xg[i]); g2[i] = dpp_ror2(xg[i]); v1[i] = dpp_ror1(xv[i]); v2[i] = dpp_ror2(xv[i]); }
;                     f32x4 pg1, pg2, pv1, pv2;
; #pragma unroll
;                     for (int i = 0; i < 4; ++i) { pg1[i] = c1 ? g1p[i] : g1[i]; pg2[i] = c2 ? g2p[i] : g2[i]; pv1[i] = c1 ? v1p[i] : v1[i]; pv2[i] = c2 ? v2p[i] : v2[i]; }
;                     const f32x4 G = wg0 * pg2 + wg1 * pg1 + wg2 * xg + bg;
;                     const f32x4 V = wv0 * pv2 + wv1 * pv1 + wv2 * xv + bv;
;                     f32x4 r;
; #pragma unroll
;                     for (int i = 0; i < 4; ++i) r[i] = G[i] * __builtin_amdgcn_rcpf(1.0f + __builtin_amdgcn_exp2f(-1.4426950408889634f * G[i])) * V[i];
;                     u32x2 w; w.x = cvt_pk_bf16(r[0], r[1]); w.y = cvt_pk_bf16(r[2], r[3]);
;                     if (m > 0 || !c2) *(u32x2*)(ACT + (size_t)(rowu + ai * HALF + m * 16) * 2816 + loff) = w;
;                     g1p = g1; g2p = g2; v1p = v1; v2p = v2;
	s_waitcnt lgkmcnt(0)
	v_pk_mul_f32 v[82:83], v[60:61], v[78:79]
	v_pk_mul_f32 v[84:85], v[44:45], v[74:75]
	v_pk_fma_f32 v[82:83], v[48:49], v[76:77], v[82:83]
	v_pk_fma_f32 v[84:85], v[32:33], v[70:71], v[84:85]
	v_pk_fma_f32 v[28:29], v[28:29], v[52:53], v[82:83]
	v_pk_fma_f32 v[24:25], v[24:25], v[36:37], v[84:85]
	v_pk_add_f32 v[28:29], v[56:57], v[28:29]
	v_pk_add_f32 v[24:25], v[40:41], v[24:25]
	v_mul_f32_e32 v82, 0xbfb8aa3b, v28
	v_mul_f32_e32 v83, 0xbfb8aa3b, v29
	v_exp_f32_e32 v82, v82
	v_exp_f32_e32 v83, v83
	s_mul_hi_i32 s3, s70, 0x1600
	s_mulk_i32 s70, 0x1600
	v_add_f32_e32 v82, 1.0, v82
	v_add_f32_e32 v83, 1.0, v83
	v_rcp_f32_e32 v82, v82
	v_rcp_f32_e32 v83, v83
	s_add_u32 s42, s79, s70
	s_addc_u32 s43, s84, s3
	v_pk_mul_f32 v[28:29], v[28:29], v[82:83]
	s_nop 0
	v_pk_mul_f32 v[24:25], v[24:25], v[28:29]
	v_pk_mul_f32 v[28:29], v[62:63], v[72:73]
	v_pk_mul_f32 v[82:83], v[46:47], v[66:67]
	v_pk_fma_f32 v[28:29], v[50:51], v[68:69], v[28:29]
	v_pk_fma_f32 v[82:83], v[34:35], v[64:65], v[82:83]
	v_pk_fma_f32 v[28:29], v[30:31], v[54:55], v[28:29]
	v_pk_fma_f32 v[26:27], v[26:27], v[38:39], v[82:83]
	v_pk_add_f32 v[28:29], v[58:59], v[28:29]
	v_pk_add_f32 v[26:27], v[42:43], v[26:27]
	v_mul_f32_e32 v30, 0xbfb8aa3b, v28
	v_mul_f32_e32 v31, 0xbfb8aa3b, v29
	v_exp_f32_e32 v30, v30
	v_exp_f32_e32 v31, v31
	v_add_f32_e32 v30, 1.0, v30
	v_add_f32_e32 v31, 1.0, v31
	v_rcp_f32_e32 v30, v30
	v_rcp_f32_e32 v31, v31
	s_nop 0
	v_pk_mul_f32 v[28:29], v[28:29], v[30:31]
	s_nop 0
	v_pk_mul_f32 v[26:27], v[26:27], v[28:29]
	s_nop 0
	v_cvt_pk_bf16_f32 v27, v26, v27
	v_cvt_pk_bf16_f32 v26, v24, v25
	v_lshl_add_u64 v[24:25], v[80:81], 1, s[42:43]
	global_store_dwordx2 v[24:25], v[26:27], off
.LBB0_578:
	s_andn2_saveexec_b64 s[40:41], s[40:41]
	s_or_b64 exec, exec, s[40:41]
	v_mov_b32_dpp v31, v20 row_ror:2 row_mask:0xf bank_mask:0xf
	v_mov_b32_dpp v85, v21 row_ror:2 row_mask:0xf bank_mask:0xf
	v_mov_b32_dpp v30, v20 row_ror:1 row_mask:0xf bank_mask:0xf
	v_mov_b32_dpp v84, v21 row_ror:1 row_mask:0xf bank_mask:0xf
	v_cndmask_b32_e32 v25, v85, v79, vcc
	v_cndmask_b32_e32 v24, v31, v78, vcc
	s_waitcnt lgkmcnt(0)
	v_pk_mul_f32 v[24:25], v[60:61], v[24:25]
	v_cndmask_b32_e64 v27, v84, v77, s[38:39]
	v_cndmask_b32_e64 v26, v30, v76, s[38:39]
	v_pk_fma_f32 v[24:25], v[48:49], v[26:27], v[24:25]
	v_mov_b32_dpp v83, v16 row_ror:2 row_mask:0xf bank_mask:0xf
	v_pk_fma_f32 v[20:21], v[20:21], v[52:53], v[24:25]
	v_mov_b32_dpp v87, v17 row_ror:2 row_mask:0xf bank_mask:0xf
	v_pk_add_f32 v[20:21], v[56:57], v[20:21]
	v_mov_b32_dpp v82, v16 row_ror:1 row_mask:0xf bank_mask:0xf
	v_mul_f32_e32 v24, 0xbfb8aa3b, v20
	v_mul_f32_e32 v25, 0xbfb8aa3b, v21
	v_exp_f32_e32 v24, v24
	v_exp_f32_e32 v25, v25
	v_mov_b32_dpp v86, v17 row_ror:1 row_mask:0xf bank_mask:0xf
	v_cndmask_b32_e32 v27, v87, v75, vcc
	v_cndmask_b32_e32 v26, v83, v74, vcc
	v_pk_mul_f32 v[26:27], v[44:45], v[26:27]
	v_cndmask_b32_e64 v29, v86, v71, s[38:39]
	v_cndmask_b32_e64 v28, v82, v70, s[38:39]
	v_mov_b32_dpp v89, v22 row_ror:2 row_mask:0xf bank_mask:0xf
	v_mov_b32_dpp v76, v23 row_ror:2 row_mask:0xf bank_mask:0xf
	v_add_f32_e32 v24, 1.0, v24
	v_pk_fma_f32 v[26:27], v[32:33], v[28:29], v[26:27]
	v_add_f32_e32 v25, 1.0, v25
	v_mov_b32_dpp v88, v22 row_ror:1 row_mask:0xf bank_mask:0xf
	v_mov_b32_dpp v92, v23 row_ror:1 row_mask:0xf bank_mask:0xf
	v_rcp_f32_e32 v24, v24
	v_pk_fma_f32 v[16:17], v[16:17], v[36:37], v[26:27]
	v_rcp_f32_e32 v25, v25
	v_cndmask_b32_e32 v27, v76, v73, vcc
	v_cndmask_b32_e32 v26, v89, v72, vcc
	v_pk_mul_f32 v[26:27], v[62:63], v[26:27]
	v_cndmask_b32_e64 v29, v92, v69, s[38:39]
	v_cndmask_b32_e64 v28, v88, v68, s[38:39]
	v_pk_fma_f32 v[26:27], v[50:51], v[28:29], v[26:27]
	v_pk_add_f32 v[16:17], v[40:41], v[16:17]
	v_pk_fma_f32 v[22:23], v[22:23], v[54:55], v[26:27]
	v_pk_mul_f32 v[20:21], v[20:21], v[24:25]
	v_pk_add_f32 v[22:23], v[58:59], v[22:23]
	v_pk_mul_f32 v[16:17], v[16:17], v[20:21]
	v_mul_f32_e32 v26, 0xbfb8aa3b, v22
	v_mul_f32_e32 v21, 0xbfb8aa3b, v23
	v_exp_f32_e32 v26, v26
	v_exp_f32_e32 v21, v21
	v_mov_b32_dpp v91, v18 row_ror:2 row_mask:0xf bank_mask:0xf
	v_mov_b32_dpp v78, v19 row_ror:2 row_mask:0xf bank_mask:0xf
	v_add_f32_e32 v20, 1.0, v26
	v_add_f32_e32 v21, 1.0, v21
	v_mov_b32_dpp v90, v18 row_ror:1 row_mask:0xf bank_mask:0xf
	v_mov_b32_dpp v77, v19 row_ror:1 row_mask:0xf bank_mask:0xf
	v_rcp_f32_e32 v20, v20
	v_cndmask_b32_e32 v25, v78, v67, vcc
	v_cndmask_b32_e32 v24, v91, v66, vcc
	v_rcp_f32_e32 v21, v21
	v_pk_mul_f32 v[24:25], v[46:47], v[24:25]
	v_cndmask_b32_e64 v27, v77, v65, s[38:39]
	v_cndmask_b32_e64 v26, v90, v64, s[38:39]
	v_pk_fma_f32 v[24:25], v[34:35], v[26:27], v[24:25]
	v_pk_mul_f32 v[20:21], v[22:23], v[20:21]
	v_pk_fma_f32 v[18:19], v[18:19], v[38:39], v[24:25]
	s_nop 0
	v_pk_add_f32 v[18:19], v[42:43], v[18:19]
	s_nop 0
	v_pk_mul_f32 v[18:19], v[18:19], v[20:21]
	s_nop 0
	v_cvt_pk_bf16_f32 v19, v18, v19
	v_cvt_pk_bf16_f32 v18, v16, v17
	v_lshlrev_b64 v[16:17], 1, v[80:81]
	v_lshl_add_u64 v[20:21], s[4:5], 0, v[16:17]
	global_store_dwordx2 v[20:21], v[18:19], off
	v_mov_b32_dpp v25, v12 row_ror:2 row_mask:0xf bank_mask:0xf
	v_mov_b32_dpp v29, v13 row_ror:2 row_mask:0xf bank_mask:0xf
	v_mov_b32_dpp v24, v12 row_ror:1 row_mask:0xf bank_mask:0xf
	v_mov_b32_dpp v28, v13 row_ror:1 row_mask:0xf bank_mask:0xf
	v_cndmask_b32_e32 v19, v29, v85, vcc
	v_cndmask_b32_e32 v18, v25, v31, vcc
	v_pk_mul_f32 v[18:19], v[60:61], v[18:19]
	v_cndmask_b32_e64 v21, v28, v84, s[38:39]
	v_cndmask_b32_e64 v20, v24, v30, s[38:39]
	v_pk_fma_f32 v[18:19], v[48:49], v[20:21], v[18:19]
	v_mov_b32_dpp v27, v8 row_ror:2 row_mask:0xf bank_mask:0xf
; __device__ __forceinline__ unsigned cvt_pk_bf16(float lo, float hi) { f32x2_cv v = {lo, hi}; bf16x2_cv b = __builtin_convertvector(v, bf16x2_cv); return __builtin_bit_cast(unsigned, b); }
; #define PG8_BAR __builtin_amdgcn_s_barrier()
;     __device__ __forceinline__ void operator()(const f32x4 (&acc)[2][2][4][2], const Unit& u, int wr, int wc, int fr_, int fq_) const {
;     ...
;                 for (int m = 0; m < 4; ++m) {
;                     const f32x4 xg = acc[ai][0][m][n], xv = acc[ai][1][m][n];
;                     f32x4 g1, g2, v1, v2;
; #pragma unroll
;                     for (int i = 0; i < 4; ++i) { g1[i] = dpp_ror1(xg[i]); g2[i] = dpp_ror2(xg[i]); v1[i] = dpp_ror1(xv[i]); v2[i] = dpp_ror2(xv[i]); }
;                     f32x4 pg1, pg2, pv1, pv2;
; #pragma unroll
;                     for (int i = 0; i < 4; ++i) { pg1[i] = c1 ? g1p[i] : g1[i]; pg2[i] = c2 ? g2p[i] : g2[i]; pv1[i] = c1 ? v1p[i] : v1[i]; pv2[i] = c2 ? v2p[i] : v2[i]; }
;                     const f32x4 G = wg0 * pg2 + wg1 * pg1 + wg2 * xg + bg;
;                     const f32x4 V = wv0 * pv2 + wv1 * pv1 + wv2 * xv + bv;
;                     f32x4 r;
; #pragma unroll
;                     for (int i = 0; i < 4; ++i) r[i] = G[i] * __builtin_amdgcn_rcpf(1.0f + __builtin_amdgcn_exp2f(-1.4426950408889634f * G[i])) * V[i];
;                     u32x2 w; w.x = cvt_pk_bf16(r[0], r[1]); w.y = cvt_pk_bf16(r[2], r[3]);
;                     if (m > 0 || !c2) *(u32x2*)(ACT + (size_t)(rowu + ai * HALF + m * 16) * 2816 + loff) = w;
;                     g1p = g1; g2p = g2; v1p = v1; v2p = v2;
;                     __builtin_amdgcn_sched_barrier(0);
;                 }
; template <class Epi, class Sched, bool ALIGN_EPI = false, bool SP2 = false, bool MID = false>
; __device__ __forceinline__ void gemm_phase(PG8_LAS unsigned char* lds, const Gemm g, const Sched& S, const Epi& E, const PG8_LAS float* mid = nullptr) {
;     ...
;         if (!has_next) break;
; #pragma unroll
;         for (int a = 0; a < 2; ++a)
; #pragma unroll
;             for (int b = 0; b < 2; ++b)
; #pragma unroll
;                 for (int m = 0; m < 4; ++m)
; #pragma unroll
;                     for (int n = 0; n < 2; ++n) acc[a][b][m][n] = (f32x4){0.f, 0.f, 0.f, 0.f};
;         cur = nxt; cA = nA; cB = nB; ++ui;
;         if constexpr (ALIGN_EPI) { if (wr == 1) PG8_BAR; }
;     }
	v_pk_fma_f32 v[12:13], v[12:13], v[52:53], v[18:19]
	v_mov_b32_dpp v65, v9 row_ror:2 row_mask:0xf bank_mask:0xf
	v_pk_add_f32 v[12:13], v[56:57], v[12:13]
	v_mov_b32_dpp v26, v8 row_ror:1 row_mask:0xf bank_mask:0xf
	v_mul_f32_e32 v18, 0xbfb8aa3b, v12
	v_mul_f32_e32 v19, 0xbfb8aa3b, v13
	v_exp_f32_e32 v18, v18
	v_exp_f32_e32 v19, v19
	v_mov_b32_dpp v64, v9 row_ror:1 row_mask:0xf bank_mask:0xf
	v_cndmask_b32_e32 v21, v65, v87, vcc
	v_add_f32_e32 v18, 1.0, v18
	v_add_f32_e32 v19, 1.0, v19
	v_rcp_f32_e32 v18, v18
	v_cndmask_b32_e32 v20, v27, v83, vcc
	v_rcp_f32_e32 v19, v19
	v_pk_mul_f32 v[20:21], v[44:45], v[20:21]
	v_cndmask_b32_e64 v23, v64, v86, s[38:39]
	v_cndmask_b32_e64 v22, v26, v82, s[38:39]
	v_pk_fma_f32 v[20:21], v[32:33], v[22:23], v[20:21]
	v_mov_b32_dpp v67, v14 row_ror:2 row_mask:0xf bank_mask:0xf
	v_pk_fma_f32 v[8:9], v[8:9], v[36:37], v[20:21]
	v_mov_b32_dpp v71, v15 row_ror:2 row_mask:0xf bank_mask:0xf
	v_pk_add_f32 v[8:9], v[40:41], v[8:9]
	v_pk_mul_f32 v[12:13], v[12:13], v[18:19]
	v_mov_b32_dpp v66, v14 row_ror:1 row_mask:0xf bank_mask:0xf
	v_mov_b32_dpp v70, v15 row_ror:1 row_mask:0xf bank_mask:0xf
	v_pk_mul_f32 v[8:9], v[8:9], v[12:13]
	v_cndmask_b32_e32 v13, v71, v76, vcc
	v_cndmask_b32_e32 v12, v67, v89, vcc
	v_pk_mul_f32 v[12:13], v[62:63], v[12:13]
	v_cndmask_b32_e64 v19, v70, v92, s[38:39]
	v_cndmask_b32_e64 v18, v66, v88, s[38:39]
	v_pk_fma_f32 v[12:13], v[50:51], v[18:19], v[12:13]
	v_mov_b32_dpp v69, v10 row_ror:2 row_mask:0xf bank_mask:0xf
	v_pk_fma_f32 v[12:13], v[14:15], v[54:55], v[12:13]
	v_mov_b32_dpp v73, v11 row_ror:2 row_mask:0xf bank_mask:0xf
	v_pk_add_f32 v[12:13], v[58:59], v[12:13]
	v_mov_b32_dpp v68, v10 row_ror:1 row_mask:0xf bank_mask:0xf
	v_mul_f32_e32 v14, 0xbfb8aa3b, v12
	v_mul_f32_e32 v15, 0xbfb8aa3b, v13
	v_exp_f32_e32 v14, v14
	v_exp_f32_e32 v15, v15
	v_mov_b32_dpp v72, v11 row_ror:1 row_mask:0xf bank_mask:0xf
	v_cndmask_b32_e32 v19, v73, v78, vcc
	v_add_f32_e32 v14, 1.0, v14
	v_add_f32_e32 v15, 1.0, v15
	v_rcp_f32_e32 v14, v14
	v_cndmask_b32_e32 v18, v69, v91, vcc
	v_rcp_f32_e32 v15, v15
	v_pk_mul_f32 v[18:19], v[46:47], v[18:19]
	v_cndmask_b32_e64 v21, v72, v77, s[38:39]
	v_cndmask_b32_e64 v20, v68, v90, s[38:39]
	v_pk_fma_f32 v[18:19], v[34:35], v[20:21], v[18:19]
	v_pk_mul_f32 v[12:13], v[12:13], v[14:15]
	v_pk_fma_f32 v[10:11], v[10:11], v[38:39], v[18:19]
	s_nop 0
	v_pk_add_f32 v[10:11], v[42:43], v[10:11]
	s_nop 0
	v_pk_mul_f32 v[10:11], v[10:11], v[12:13]
	s_nop 0
	v_cvt_pk_bf16_f32 v11, v10, v11
	v_cvt_pk_bf16_f32 v10, v8, v9
	v_lshl_add_u64 v[8:9], s[12:13], 0, v[16:17]
	global_store_dwordx2 v[8:9], v[10:11], off
	s_nop 0
	v_mov_b32_dpp v8, v4 row_ror:2 row_mask:0xf bank_mask:0xf
	v_mov_b32_dpp v9, v5 row_ror:2 row_mask:0xf bank_mask:0xf
	v_mov_b32_dpp v10, v4 row_ror:1 row_mask:0xf bank_mask:0xf
	v_mov_b32_dpp v11, v5 row_ror:1 row_mask:0xf bank_mask:0xf
	v_cndmask_b32_e32 v9, v9, v29, vcc
	v_cndmask_b32_e32 v8, v8, v25, vcc
	v_pk_mul_f32 v[8:9], v[60:61], v[8:9]
	v_cndmask_b32_e64 v11, v11, v28, s[38:39]
	v_cndmask_b32_e64 v10, v10, v24, s[38:39]
	v_pk_fma_f32 v[8:9], v[48:49], v[10:11], v[8:9]
	v_mov_b32_dpp v13, v0 row_ror:2 row_mask:0xf bank_mask:0xf
	v_pk_fma_f32 v[4:5], v[4:5], v[52:53], v[8:9]
	v_mov_b32_dpp v15, v1 row_ror:2 row_mask:0xf bank_mask:0xf
	v_pk_add_f32 v[4:5], v[56:57], v[4:5]
	v_mov_b32_dpp v12, v0 row_ror:1 row_mask:0xf bank_mask:0xf
	v_mul_f32_e32 v8, 0xbfb8aa3b, v4
	v_mul_f32_e32 v9, 0xbfb8aa3b, v5
	v_exp_f32_e32 v8, v8
	v_exp_f32_e32 v9, v9
	v_mov_b32_dpp v14, v1 row_ror:1 row_mask:0xf bank_mask:0xf
	v_cndmask_b32_e32 v11, v15, v65, vcc
	v_cndmask_b32_e32 v10, v13, v27, vcc
	v_pk_mul_f32 v[10:11], v[44:45], v[10:11]
	v_cndmask_b32_e64 v13, v14, v64, s[38:39]
	v_cndmask_b32_e64 v12, v12, v26, s[38:39]
	v_mov_b32_dpp v19, v6 row_ror:2 row_mask:0xf bank_mask:0xf
	v_mov_b32_dpp v23, v7 row_ror:2 row_mask:0xf bank_mask:0xf
	v_add_f32_e32 v8, 1.0, v8
	v_pk_fma_f32 v[10:11], v[32:33], v[12:13], v[10:11]
	v_add_f32_e32 v9, 1.0, v9
	v_mov_b32_dpp v18, v6 row_ror:1 row_mask:0xf bank_mask:0xf
	v_mov_b32_dpp v22, v7 row_ror:1 row_mask:0xf bank_mask:0xf
	v_rcp_f32_e32 v8, v8
	v_pk_fma_f32 v[0:1], v[0:1], v[36:37], v[10:11]
	v_rcp_f32_e32 v9, v9
	v_cndmask_b32_e32 v11, v23, v71, vcc
	v_cndmask_b32_e32 v10, v19, v67, vcc
	v_pk_mul_f32 v[10:11], v[62:63], v[10:11]
	v_cndmask_b32_e64 v13, v22, v70, s[38:39]
	v_cndmask_b32_e64 v12, v18, v66, s[38:39]
	v_pk_fma_f32 v[10:11], v[50:51], v[12:13], v[10:11]
	v_pk_add_f32 v[0:1], v[40:41], v[0:1]
	v_pk_fma_f32 v[6:7], v[6:7], v[54:55], v[10:11]
	v_pk_mul_f32 v[4:5], v[4:5], v[8:9]
	v_pk_add_f32 v[6:7], v[58:59], v[6:7]
	v_pk_mul_f32 v[0:1], v[0:1], v[4:5]
	v_mul_f32_e32 v10, 0xbfb8aa3b, v6
	v_mul_f32_e32 v5, 0xbfb8aa3b, v7
	v_exp_f32_e32 v10, v10
	v_exp_f32_e32 v5, v5
	v_mov_b32_dpp v21, v2 row_ror:2 row_mask:0xf bank_mask:0xf
	v_mov_b32_dpp v25, v3 row_ror:2 row_mask:0xf bank_mask:0xf
	v_add_f32_e32 v4, 1.0, v10
	v_add_f32_e32 v5, 1.0, v5
	v_mov_b32_dpp v20, v2 row_ror:1 row_mask:0xf bank_mask:0xf
	v_mov_b32_dpp v24, v3 row_ror:1 row_mask:0xf bank_mask:0xf
	v_rcp_f32_e32 v4, v4
	v_cndmask_b32_e32 v9, v25, v73, vcc
	v_cndmask_b32_e32 v8, v21, v69, vcc
	v_rcp_f32_e32 v5, v5
	v_pk_mul_f32 v[8:9], v[46:47], v[8:9]
	v_cndmask_b32_e64 v11, v24, v72, s[38:39]
	v_cndmask_b32_e64 v10, v20, v68, s[38:39]
	v_pk_fma_f32 v[8:9], v[34:35], v[10:11], v[8:9]
	v_pk_mul_f32 v[4:5], v[6:7], v[4:5]
	v_pk_fma_f32 v[2:3], v[2:3], v[38:39], v[8:9]
	s_nop 0
	v_pk_add_f32 v[2:3], v[42:43], v[2:3]
	s_nop 0
	v_pk_mul_f32 v[2:3], v[2:3], v[4:5]
	s_nop 0
	v_cvt_pk_bf16_f32 v3, v2, v3
	v_cvt_pk_bf16_f32 v2, v0, v1
	v_lshl_add_u64 v[0:1], s[20:21], 0, v[16:17]
	global_store_dwordx2 v[0:1], v[2:3], off
	s_andn2_b64 vcc, exec, s[36:37]
	s_mov_b64 s[4:5], -1
	s_cbranch_vccnz .LBB0_555
	v_readlane_b32 s4, v255, 51
	v_readlane_b32 s5, v255, 52
	s_andn2_b64 vcc, exec, s[4:5]
	s_cbranch_vccnz .LBB0_554
	s_barrier
	s_branch .LBB0_554

; __global__ void __launch_bounds__(NWAVES * 64, 2) fwd_megakernel(Args args) {
	.amdhsa_kernel _Z14fwd_megakernel4Args
		.amdhsa_group_segment_fixed_size 0
		.amdhsa_private_segment_fixed_size 0
		.amdhsa_kernarg_size 384
		.amdhsa_user_sgpr_count 2
		.amdhsa_user_sgpr_dispatch_ptr 0
		.amdhsa_user_sgpr_queue_ptr 0
		.amdhsa_user_sgpr_kernarg_segment_ptr 1
		.amdhsa_user_sgpr_dispatch_id 0
		.amdhsa_user_sgpr_kernarg_preload_length 0
		.amdhsa_user_sgpr_kernarg_preload_offset 0
		.amdhsa_user_sgpr_private_segment_size 0
		.amdhsa_uses_dynamic_stack 0
		.amdhsa_enable_private_segment 0
		.amdhsa_system_sgpr_workgroup_id_x 1
		.amdhsa_system_sgpr_workgroup_id_y 0
		.amdhsa_system_sgpr_workgroup_id_z 0
		.amdhsa_system_sgpr_workgroup_info 0
		.amdhsa_system_vgpr_workitem_id 2
		.amdhsa_next_free_vgpr 256
		.amdhsa_next_free_sgpr 102
		.amdhsa_accum_offset 256
		.amdhsa_reserve_vcc 1
		.amdhsa_float_round_mode_32 0
		.amdhsa_float_round_mode_16_64 0
		.amdhsa_float_denorm_mode_32 3
		.amdhsa_float_denorm_mode_16_64 3
		.amdhsa_dx10_clamp 1
		.amdhsa_ieee_mode 1
		.amdhsa_fp16_overflow 0
		.amdhsa_tg_split 0
		.amdhsa_exception_fp_ieee_invalid_op 0
		.amdhsa_exception_fp_denorm_src 0
		.amdhsa_exception_fp_ieee_div_zero 0
		.amdhsa_exception_fp_ieee_overflow 0
		.amdhsa_exception_fp_ieee_underflow 0
		.amdhsa_exception_fp_ieee_inexact 0
		.amdhsa_exception_int_div_zero 0
	.end_amdhsa_kernel

; __global__ void __launch_bounds__(NWAVES * 64, 2) fwd_megakernel(Args args) {
amdhsa.kernels:
  - .agpr_count:     0
    .args:
      - .offset:         0
        .size:           128
        .value_kind:     by_value
      - .offset:         128
        .size:           4
        .value_kind:     hidden_block_count_x
      - .offset:         132
        .size:           4
        .value_kind:     hidden_block_count_y
      - .offset:         136
        .size:           4
        .value_kind:     hidden_block_count_z
      - .offset:         140
        .size:           2
        .value_kind:     hidden_group_size_x
      - .offset:         142
        .size:           2
        .value_kind:     hidden_group_size_y
      - .offset:         144
        .size:           2
        .value_kind:     hidden_group_size_z
      - .offset:         146
        .size:           2
        .value_kind:     hidden_remainder_x
      - .offset:         148
        .size:           2
        .value_kind:     hidden_remainder_y
      - .offset:         150
        .size:           2
        .value_kind:     hidden_remainder_z
      - .offset:         168
        .size:           8
        .value_kind:     hidden_global_offset_x
      - .offset:         176
        .size:           8
        .value_kind:     hidden_global_offset_y
      - .offset:         184
        .size:           8
        .value_kind:     hidden_global_offset_z
      - .offset:         192
        .size:           2
        .value_kind:     hidden_grid_dims
      - .offset:         216
        .size:           8
        .value_kind:     hidden_multigrid_sync_arg
      - .offset:         248
        .size:           4
        .value_kind:     hidden_dynamic_lds_size
    .group_segment_fixed_size: 0
    .kernarg_segment_align: 8
    .kernarg_segment_size: 384
    .language:       OpenCL C
    .language_version:
      - 2
      - 0
    .max_flat_workgroup_size: 512
    .name:           _Z14fwd_megakernel4Args
    .private_segment_fixed_size: 0
    .sgpr_count:     108
    .sgpr_spill_count: 122
    .symbol:         _Z14fwd_megakernel4Args.kd
    .uniform_work_group_size: 1
    .uses_dynamic_stack: false
    .vgpr_count:     256
    .vgpr_spill_count: 0
    .wavefront_size: 64
